# S5 phase: A-operand (EE/MF) global loads prefetched in bulk instead of one exposed L2 round trip per k-step; carry scan reads issued 8 steps ahead; LDS reads pipelined
# speedup vs baseline: 1.0154x; 1.0149x over previous
.LBB0_719:
	v_add_lshl_u32 v34, v119, s88, 8
	v_ashrrev_i32_e32 v35, 31, v34
	v_lshl_add_u64 v[34:35], v[34:35], 1, v[150:151]
	global_load_dwordx4 v[44:47], v[34:35], off
	global_load_dwordx4 v[166:169], v[34:35], off offset:32
	global_load_dwordx4 v[170:173], v[34:35], off offset:64
	global_load_dwordx4 v[174:177], v[34:35], off offset:96
	global_load_dwordx4 v[190:193], v[34:35], off offset:128
	global_load_dwordx4 v[194:197], v[34:35], off offset:160
	global_load_dwordx4 v[198:201], v[34:35], off offset:192
	global_load_dwordx4 v[202:205], v[34:35], off offset:224
	global_load_dwordx4 v[206:209], v[34:35], off offset:256
	global_load_dwordx4 v[234:237], v[34:35], off offset:288
	global_load_dwordx4 v[238:241], v[34:35], off offset:320
	global_load_dwordx4 v[242:245], v[34:35], off offset:352
	v_add_u32_e32 v32, v139, v141
	ds_read_b128 v[36:39], v32
	ds_read_b128 v[40:43], v32 offset:16896
	ds_read_b128 v[246:249], v32 offset:32
	ds_read_b128 v[250:253], v32 offset:16928
	s_waitcnt vmcnt(11) lgkmcnt(3)
	v_mfma_f32_32x32x16_bf16 v[96:111], v[44:47], v[36:39], 0
	ds_read_b128 v[36:39], v32 offset:64
	s_waitcnt lgkmcnt(3)
	v_mfma_f32_32x32x16_bf16 v[80:95], v[44:47], v[40:43], 0
	ds_read_b128 v[40:43], v32 offset:16960
	s_waitcnt vmcnt(10) lgkmcnt(3)
	v_mfma_f32_32x32x16_bf16 v[96:111], v[166:169], v[246:249], v[96:111]
	ds_read_b128 v[246:249], v32 offset:96
	s_waitcnt lgkmcnt(3)
	v_mfma_f32_32x32x16_bf16 v[80:95], v[166:169], v[250:253], v[80:95]
	ds_read_b128 v[250:253], v32 offset:16992
	global_load_dwordx4 v[44:47], v[34:35], off offset:384
	s_waitcnt vmcnt(10) lgkmcnt(3)
	v_mfma_f32_32x32x16_bf16 v[96:111], v[170:173], v[36:39], v[96:111]
	ds_read_b128 v[36:39], v32 offset:128
	s_waitcnt lgkmcnt(3)
	v_mfma_f32_32x32x16_bf16 v[80:95], v[170:173], v[40:43], v[80:95]
	ds_read_b128 v[40:43], v32 offset:17024
	global_load_dwordx4 v[166:169], v[34:35], off offset:416
	s_waitcnt vmcnt(10) lgkmcnt(3)
	v_mfma_f32_32x32x16_bf16 v[96:111], v[174:177], v[246:249], v[96:111]
	ds_read_b128 v[246:249], v32 offset:160
	s_waitcnt lgkmcnt(3)
	v_mfma_f32_32x32x16_bf16 v[80:95], v[174:177], v[250:253], v[80:95]
	ds_read_b128 v[250:253], v32 offset:17056
	global_load_dwordx4 v[170:173], v[34:35], off offset:448
	s_waitcnt vmcnt(10) lgkmcnt(3)
	v_mfma_f32_32x32x16_bf16 v[96:111], v[190:193], v[36:39], v[96:111]
	ds_read_b128 v[36:39], v32 offset:192
	s_waitcnt lgkmcnt(3)
	v_mfma_f32_32x32x16_bf16 v[80:95], v[190:193], v[40:43], v[80:95]
	ds_read_b128 v[40:43], v32 offset:17088
	global_load_dwordx4 v[174:177], v[34:35], off offset:480
	s_waitcnt vmcnt(10) lgkmcnt(3)
	v_mfma_f32_32x32x16_bf16 v[96:111], v[194:197], v[246:249], v[96:111]
	ds_read_b128 v[246:249], v32 offset:224
	s_waitcnt lgkmcnt(3)
	v_mfma_f32_32x32x16_bf16 v[80:95], v[194:197], v[250:253], v[80:95]
	ds_read_b128 v[250:253], v32 offset:17120
	s_waitcnt vmcnt(9) lgkmcnt(3)
	v_mfma_f32_32x32x16_bf16 v[96:111], v[198:201], v[36:39], v[96:111]
	ds_read_b128 v[36:39], v32 offset:256
	s_waitcnt lgkmcnt(3)
	v_mfma_f32_32x32x16_bf16 v[80:95], v[198:201], v[40:43], v[80:95]
	ds_read_b128 v[40:43], v32 offset:17152
	s_waitcnt vmcnt(8) lgkmcnt(3)
	v_mfma_f32_32x32x16_bf16 v[96:111], v[202:205], v[246:249], v[96:111]
	ds_read_b128 v[246:249], v32 offset:288
	s_waitcnt lgkmcnt(3)
	v_mfma_f32_32x32x16_bf16 v[80:95], v[202:205], v[250:253], v[80:95]
	ds_read_b128 v[250:253], v32 offset:17184
	s_waitcnt vmcnt(7) lgkmcnt(3)
	v_mfma_f32_32x32x16_bf16 v[96:111], v[206:209], v[36:39], v[96:111]
	ds_read_b128 v[36:39], v32 offset:320
	s_waitcnt lgkmcnt(3)
	v_mfma_f32_32x32x16_bf16 v[80:95], v[206:209], v[40:43], v[80:95]
	ds_read_b128 v[40:43], v32 offset:17216
	s_waitcnt vmcnt(6) lgkmcnt(3)
	v_mfma_f32_32x32x16_bf16 v[96:111], v[234:237], v[246:249], v[96:111]
	ds_read_b128 v[246:249], v32 offset:352
	s_waitcnt lgkmcnt(3)
	v_mfma_f32_32x32x16_bf16 v[80:95], v[234:237], v[250:253], v[80:95]
	ds_read_b128 v[250:253], v32 offset:17248
	s_waitcnt vmcnt(5) lgkmcnt(3)
	v_mfma_f32_32x32x16_bf16 v[96:111], v[238:241], v[36:39], v[96:111]
	ds_read_b128 v[36:39], v32 offset:384
	s_waitcnt lgkmcnt(3)
	v_mfma_f32_32x32x16_bf16 v[80:95], v[238:241], v[40:43], v[80:95]
	ds_read_b128 v[40:43], v32 offset:17280
	s_waitcnt vmcnt(4) lgkmcnt(3)
	v_mfma_f32_32x32x16_bf16 v[96:111], v[242:245], v[246:249], v[96:111]
	ds_read_b128 v[246:249], v32 offset:416
	s_waitcnt lgkmcnt(3)
	v_mfma_f32_32x32x16_bf16 v[80:95], v[242:245], v[250:253], v[80:95]
	ds_read_b128 v[250:253], v32 offset:17312
	s_waitcnt vmcnt(3) lgkmcnt(3)
	v_mfma_f32_32x32x16_bf16 v[96:111], v[44:47], v[36:39], v[96:111]
	ds_read_b128 v[36:39], v32 offset:448
	s_waitcnt lgkmcnt(3)
	v_mfma_f32_32x32x16_bf16 v[80:95], v[44:47], v[40:43], v[80:95]
	ds_read_b128 v[40:43], v32 offset:17344
	s_waitcnt vmcnt(2) lgkmcnt(3)
	v_mfma_f32_32x32x16_bf16 v[96:111], v[166:169], v[246:249], v[96:111]
	ds_read_b128 v[246:249], v32 offset:480
	s_waitcnt lgkmcnt(3)
	v_mfma_f32_32x32x16_bf16 v[80:95], v[166:169], v[250:253], v[80:95]
	ds_read_b128 v[250:253], v32 offset:17376
	s_waitcnt vmcnt(1) lgkmcnt(3)
	v_mfma_f32_32x32x16_bf16 v[96:111], v[170:173], v[36:39], v[96:111]
	s_waitcnt lgkmcnt(2)
	v_mfma_f32_32x32x16_bf16 v[80:95], v[170:173], v[40:43], v[80:95]
	s_waitcnt vmcnt(0) lgkmcnt(1)
	v_mfma_f32_32x32x16_bf16 v[96:111], v[174:177], v[246:249], v[96:111]
	s_waitcnt lgkmcnt(0)
	v_mfma_f32_32x32x16_bf16 v[80:95], v[174:177], v[250:253], v[80:95]
	s_nop 11
	ds_write_b128 v165, v[96:99]
	ds_write_b128 v165, v[100:103] offset:32
	ds_write_b128 v165, v[104:107] offset:64
	ds_write_b128 v165, v[108:111] offset:96
	ds_write_b128 v165, v[80:83] offset:16896
	ds_write_b128 v165, v[84:87] offset:16928
	ds_write_b128 v165, v[88:91] offset:16960
	ds_write_b128 v165, v[92:95] offset:16992
	s_waitcnt lgkmcnt(0)
	s_barrier
	s_and_b64 s[30:31], s[10:11], exec
	s_cbranch_scc0 .Ls5_nopf
	global_load_dwordx4 v[100:103], v[148:149], off
	global_load_dwordx4 v[104:107], v[148:149], off offset:32
	global_load_dwordx4 v[108:111], v[148:149], off offset:64
	global_load_dwordx4 v[166:169], v[148:149], off offset:96
	global_load_dwordx4 v[170:173], v[148:149], off offset:128
	global_load_dwordx4 v[174:177], v[148:149], off offset:160
	global_load_dwordx4 v[190:193], v[148:149], off offset:192
	global_load_dwordx4 v[194:197], v[148:149], off offset:224
	global_load_dwordx4 v[198:201], v[148:149], off offset:256
	global_load_dwordx4 v[202:205], v[148:149], off offset:288
	global_load_dwordx4 v[206:209], v[148:149], off offset:320
	global_load_dwordx4 v[234:237], v[148:149], off offset:352
	global_load_dwordx4 v[238:241], v[148:149], off offset:384
	global_load_dwordx4 v[242:245], v[148:149], off offset:416
	global_load_dwordx4 v[246:249], v[148:149], off offset:448
	global_load_dwordx4 v[250:253], v[148:149], off offset:480
.Ls5_nopf:
	s_and_saveexec_b64 s[8:9], s[2:3]
	s_cbranch_execz .LBB0_722
	v_or_b32_e32 v32, s88, v147
	v_lshl_add_u64 v[34:35], v[32:33], 2, s[0:1]
	global_load_dwordx2 v[34:35], v[34:35], off
	s_and_b64 s[30:31], s[10:11], exec
	s_cselect_b32 s24, 0, 0x105f0
	s_movk_i32 s25, 0x210
	s_cselect_b32 s25, s25, 0xfffffdf0
	v_add_u32_e32 v40, s24, v155
	v_add_u32_e32 v41, s25, v40
	v_add_u32_e32 v42, s25, v41
	v_add_u32_e32 v43, s25, v42
	v_add_u32_e32 v44, s25, v43
	v_add_u32_e32 v45, s25, v44
	v_add_u32_e32 v46, s25, v45
	v_add_u32_e32 v47, s25, v46
	s_lshl_b32 s24, s25, 3
	ds_read2st64_b32 v[80:81], v40 offset1:1
	ds_read2st64_b32 v[82:83], v41 offset1:1
	ds_read2st64_b32 v[84:85], v42 offset1:1
	ds_read2st64_b32 v[86:87], v43 offset1:1
	ds_read2st64_b32 v[88:89], v44 offset1:1
	ds_read2st64_b32 v[90:91], v45 offset1:1
	ds_read2st64_b32 v[92:93], v46 offset1:1
	ds_read2st64_b32 v[94:95], v47 offset1:1
	v_mov_b32_e32 v38, 0
	v_mov_b32_e32 v39, 0
	s_mov_b32 s7, 16
	s_waitcnt vmcnt(0) lgkmcnt(0)
.Ls5_scan:
	s_waitcnt lgkmcnt(14)
	ds_write2st64_b32 v40, v38, v39 offset1:1
	v_mul_f32_e32 v36, v35, v39
	v_mul_f32_e32 v37, v35, v38
	v_fma_f32 v36, v34, v38, -v36
	v_fma_f32 v37, v34, v39, v37
	v_add_f32_e32 v38, v36, v80
	v_add_f32_e32 v39, v37, v81
	v_add_u32_e32 v40, s24, v40
	ds_read2st64_b32 v[80:81], v40 offset1:1
	s_waitcnt lgkmcnt(14)
	ds_write2st64_b32 v41, v38, v39 offset1:1
	v_mul_f32_e32 v36, v35, v39
	v_mul_f32_e32 v37, v35, v38
	v_fma_f32 v36, v34, v38, -v36
	v_fma_f32 v37, v34, v39, v37
	v_add_f32_e32 v38, v36, v82
	v_add_f32_e32 v39, v37, v83
	v_add_u32_e32 v41, s24, v41
	ds_read2st64_b32 v[82:83], v41 offset1:1
	s_waitcnt lgkmcnt(14)
	ds_write2st64_b32 v42, v38, v39 offset1:1
	v_mul_f32_e32 v36, v35, v39
	v_mul_f32_e32 v37, v35, v38
	v_fma_f32 v36, v34, v38, -v36
	v_fma_f32 v37, v34, v39, v37
	v_add_f32_e32 v38, v36, v84
	v_add_f32_e32 v39, v37, v85
	v_add_u32_e32 v42, s24, v42
	ds_read2st64_b32 v[84:85], v42 offset1:1
	s_waitcnt lgkmcnt(14)
	ds_write2st64_b32 v43, v38, v39 offset1:1
	v_mul_f32_e32 v36, v35, v39
	v_mul_f32_e32 v37, v35, v38
	v_fma_f32 v36, v34, v38, -v36
	v_fma_f32 v37, v34, v39, v37
	v_add_f32_e32 v38, v36, v86
	v_add_f32_e32 v39, v37, v87
	v_add_u32_e32 v43, s24, v43
	ds_read2st64_b32 v[86:87], v43 offset1:1
	s_waitcnt lgkmcnt(14)
	ds_write2st64_b32 v44, v38, v39 offset1:1
	v_mul_f32_e32 v36, v35, v39
	v_mul_f32_e32 v37, v35, v38
	v_fma_f32 v36, v34, v38, -v36
	v_fma_f32 v37, v34, v39, v37
	v_add_f32_e32 v38, v36, v88
	v_add_f32_e32 v39, v37, v89
	v_add_u32_e32 v44, s24, v44
	ds_read2st64_b32 v[88:89], v44 offset1:1
	s_waitcnt lgkmcnt(14)
	ds_write2st64_b32 v45, v38, v39 offset1:1
	v_mul_f32_e32 v36, v35, v39
	v_mul_f32_e32 v37, v35, v38
	v_fma_f32 v36, v34, v38, -v36
	v_fma_f32 v37, v34, v39, v37
	v_add_f32_e32 v38, v36, v90
	v_add_f32_e32 v39, v37, v91
	v_add_u32_e32 v45, s24, v45
	ds_read2st64_b32 v[90:91], v45 offset1:1
	s_waitcnt lgkmcnt(14)
	ds_write2st64_b32 v46, v38, v39 offset1:1
	v_mul_f32_e32 v36, v35, v39
	v_mul_f32_e32 v37, v35, v38
	v_fma_f32 v36, v34, v38, -v36
	v_fma_f32 v37, v34, v39, v37
	v_add_f32_e32 v38, v36, v92
	v_add_f32_e32 v39, v37, v93
	v_add_u32_e32 v46, s24, v46
	ds_read2st64_b32 v[92:93], v46 offset1:1
	s_waitcnt lgkmcnt(14)
	ds_write2st64_b32 v47, v38, v39 offset1:1
	v_mul_f32_e32 v36, v35, v39
	v_mul_f32_e32 v37, v35, v38
	v_fma_f32 v36, v34, v38, -v36
	v_fma_f32 v37, v34, v39, v37
	v_add_f32_e32 v38, v36, v94
	v_add_f32_e32 v39, v37, v95
	v_add_u32_e32 v47, s24, v47
	ds_read2st64_b32 v[94:95], v47 offset1:1
	s_add_i32 s7, s7, -1
	s_cmp_lg_u32 s7, 0
	s_cbranch_scc1 .Ls5_scan
.LBB0_722:
	s_or_b64 exec, exec, s[8:9]
	s_xor_b64 s[8:9], s[10:11], -1
	s_andn2_b64 vcc, exec, s[10:11]
	s_cbranch_vccnz .LBB0_724
	ds_read_b128 v[80:83], v154
	ds_read_b128 v[84:87], v154 offset:16896
	ds_read_b128 v[88:91], v154 offset:33792
	ds_read_b128 v[92:95], v154 offset:50688
	s_waitcnt vmcnt(15) lgkmcnt(3)
	v_mfma_f32_32x32x16_bf16 v[64:79], v[100:103], v[80:83], v[64:79]
	ds_read_b128 v[80:83], v154 offset:32
	s_waitcnt lgkmcnt(3)
	v_mfma_f32_32x32x16_bf16 v[48:63], v[100:103], v[84:87], v[48:63]
	ds_read_b128 v[84:87], v154 offset:16928
	s_waitcnt lgkmcnt(3)
	v_mfma_f32_32x32x16_bf16 v[16:31], v[100:103], v[88:91], v[16:31]
	ds_read_b128 v[88:91], v154 offset:33824
	s_waitcnt lgkmcnt(3)
	v_mfma_f32_32x32x16_bf16 v[0:15], v[100:103], v[92:95], v[0:15]
	ds_read_b128 v[92:95], v154 offset:50720
	s_waitcnt vmcnt(14) lgkmcnt(3)
	v_mfma_f32_32x32x16_bf16 v[64:79], v[104:107], v[80:83], v[64:79]
	ds_read_b128 v[80:83], v154 offset:64
	s_waitcnt lgkmcnt(3)
	v_mfma_f32_32x32x16_bf16 v[48:63], v[104:107], v[84:87], v[48:63]
	ds_read_b128 v[84:87], v154 offset:16960
	s_waitcnt lgkmcnt(3)
	v_mfma_f32_32x32x16_bf16 v[16:31], v[104:107], v[88:91], v[16:31]
	ds_read_b128 v[88:91], v154 offset:33856
	s_waitcnt lgkmcnt(3)
	v_mfma_f32_32x32x16_bf16 v[0:15], v[104:107], v[92:95], v[0:15]
	ds_read_b128 v[92:95], v154 offset:50752
	s_waitcnt vmcnt(13) lgkmcnt(3)
	v_mfma_f32_32x32x16_bf16 v[64:79], v[108:111], v[80:83], v[64:79]
	ds_read_b128 v[80:83], v154 offset:96
	s_waitcnt lgkmcnt(3)
	v_mfma_f32_32x32x16_bf16 v[48:63], v[108:111], v[84:87], v[48:63]
	ds_read_b128 v[84:87], v154 offset:16992
	s_waitcnt lgkmcnt(3)
	v_mfma_f32_32x32x16_bf16 v[16:31], v[108:111], v[88:91], v[16:31]
	ds_read_b128 v[88:91], v154 offset:33888
	s_waitcnt lgkmcnt(3)
	v_mfma_f32_32x32x16_bf16 v[0:15], v[108:111], v[92:95], v[0:15]
	ds_read_b128 v[92:95], v154 offset:50784
	s_waitcnt vmcnt(12) lgkmcnt(3)
	v_mfma_f32_32x32x16_bf16 v[64:79], v[166:169], v[80:83], v[64:79]
	ds_read_b128 v[80:83], v154 offset:128
	s_waitcnt lgkmcnt(3)
	v_mfma_f32_32x32x16_bf16 v[48:63], v[166:169], v[84:87], v[48:63]
	ds_read_b128 v[84:87], v154 offset:17024
	s_waitcnt lgkmcnt(3)
	v_mfma_f32_32x32x16_bf16 v[16:31], v[166:169], v[88:91], v[16:31]
	ds_read_b128 v[88:91], v154 offset:33920
	s_waitcnt lgkmcnt(3)
	v_mfma_f32_32x32x16_bf16 v[0:15], v[166:169], v[92:95], v[0:15]
	ds_read_b128 v[92:95], v154 offset:50816
	s_waitcnt vmcnt(11) lgkmcnt(3)
	v_mfma_f32_32x32x16_bf16 v[64:79], v[170:173], v[80:83], v[64:79]
	ds_read_b128 v[80:83], v154 offset:160
	s_waitcnt lgkmcnt(3)
	v_mfma_f32_32x32x16_bf16 v[48:63], v[170:173], v[84:87], v[48:63]
	ds_read_b128 v[84:87], v154 offset:17056
	s_waitcnt lgkmcnt(3)
	v_mfma_f32_32x32x16_bf16 v[16:31], v[170:173], v[88:91], v[16:31]
	ds_read_b128 v[88:91], v154 offset:33952
	s_waitcnt lgkmcnt(3)
	v_mfma_f32_32x32x16_bf16 v[0:15], v[170:173], v[92:95], v[0:15]
	ds_read_b128 v[92:95], v154 offset:50848
	s_waitcnt vmcnt(10) lgkmcnt(3)
	v_mfma_f32_32x32x16_bf16 v[64:79], v[174:177], v[80:83], v[64:79]
	ds_read_b128 v[80:83], v154 offset:192
	s_waitcnt lgkmcnt(3)
	v_mfma_f32_32x32x16_bf16 v[48:63], v[174:177], v[84:87], v[48:63]
	ds_read_b128 v[84:87], v154 offset:17088
	s_waitcnt lgkmcnt(3)
	v_mfma_f32_32x32x16_bf16 v[16:31], v[174:177], v[88:91], v[16:31]
	ds_read_b128 v[88:91], v154 offset:33984
	s_waitcnt lgkmcnt(3)
	v_mfma_f32_32x32x16_bf16 v[0:15], v[174:177], v[92:95], v[0:15]
	ds_read_b128 v[92:95], v154 offset:50880
	s_waitcnt vmcnt(9) lgkmcnt(3)
	v_mfma_f32_32x32x16_bf16 v[64:79], v[190:193], v[80:83], v[64:79]
	ds_read_b128 v[80:83], v154 offset:224
	s_waitcnt lgkmcnt(3)
	v_mfma_f32_32x32x16_bf16 v[48:63], v[190:193], v[84:87], v[48:63]
	ds_read_b128 v[84:87], v154 offset:17120
	s_waitcnt lgkmcnt(3)
	v_mfma_f32_32x32x16_bf16 v[16:31], v[190:193], v[88:91], v[16:31]
	ds_read_b128 v[88:91], v154 offset:34016
	s_waitcnt lgkmcnt(3)
	v_mfma_f32_32x32x16_bf16 v[0:15], v[190:193], v[92:95], v[0:15]
	ds_read_b128 v[92:95], v154 offset:50912
	s_waitcnt vmcnt(8) lgkmcnt(3)
	v_mfma_f32_32x32x16_bf16 v[64:79], v[194:197], v[80:83], v[64:79]
	ds_read_b128 v[80:83], v154 offset:256
	s_waitcnt lgkmcnt(3)
	v_mfma_f32_32x32x16_bf16 v[48:63], v[194:197], v[84:87], v[48:63]
	ds_read_b128 v[84:87], v154 offset:17152
	s_waitcnt lgkmcnt(3)
	v_mfma_f32_32x32x16_bf16 v[16:31], v[194:197], v[88:91], v[16:31]
	ds_read_b128 v[88:91], v154 offset:34048
	s_waitcnt lgkmcnt(3)
	v_mfma_f32_32x32x16_bf16 v[0:15], v[194:197], v[92:95], v[0:15]
	ds_read_b128 v[92:95], v154 offset:50944
	s_waitcnt vmcnt(7) lgkmcnt(3)
	v_mfma_f32_32x32x16_bf16 v[64:79], v[198:201], v[80:83], v[64:79]
	ds_read_b128 v[80:83], v154 offset:288
	s_waitcnt lgkmcnt(3)
	v_mfma_f32_32x32x16_bf16 v[48:63], v[198:201], v[84:87], v[48:63]
	ds_read_b128 v[84:87], v154 offset:17184
	s_waitcnt lgkmcnt(3)
	v_mfma_f32_32x32x16_bf16 v[16:31], v[198:201], v[88:91], v[16:31]
	ds_read_b128 v[88:91], v154 offset:34080
	s_waitcnt lgkmcnt(3)
	v_mfma_f32_32x32x16_bf16 v[0:15], v[198:201], v[92:95], v[0:15]
	ds_read_b128 v[92:95], v154 offset:50976
	s_waitcnt vmcnt(6) lgkmcnt(3)
	v_mfma_f32_32x32x16_bf16 v[64:79], v[202:205], v[80:83], v[64:79]
	ds_read_b128 v[80:83], v154 offset:320
	s_waitcnt lgkmcnt(3)
	v_mfma_f32_32x32x16_bf16 v[48:63], v[202:205], v[84:87], v[48:63]
	ds_read_b128 v[84:87], v154 offset:17216
	s_waitcnt lgkmcnt(3)
	v_mfma_f32_32x32x16_bf16 v[16:31], v[202:205], v[88:91], v[16:31]
	ds_read_b128 v[88:91], v154 offset:34112
	s_waitcnt lgkmcnt(3)
	v_mfma_f32_32x32x16_bf16 v[0:15], v[202:205], v[92:95], v[0:15]
	ds_read_b128 v[92:95], v154 offset:51008
	s_waitcnt vmcnt(5) lgkmcnt(3)
	v_mfma_f32_32x32x16_bf16 v[64:79], v[206:209], v[80:83], v[64:79]
	ds_read_b128 v[80:83], v154 offset:352
	s_waitcnt lgkmcnt(3)
	v_mfma_f32_32x32x16_bf16 v[48:63], v[206:209], v[84:87], v[48:63]
	ds_read_b128 v[84:87], v154 offset:17248
	s_waitcnt lgkmcnt(3)
	v_mfma_f32_32x32x16_bf16 v[16:31], v[206:209], v[88:91], v[16:31]
	ds_read_b128 v[88:91], v154 offset:34144
	s_waitcnt lgkmcnt(3)
	v_mfma_f32_32x32x16_bf16 v[0:15], v[206:209], v[92:95], v[0:15]
	ds_read_b128 v[92:95], v154 offset:51040
	s_waitcnt vmcnt(4) lgkmcnt(3)
	v_mfma_f32_32x32x16_bf16 v[64:79], v[234:237], v[80:83], v[64:79]
	ds_read_b128 v[80:83], v154 offset:384
	s_waitcnt lgkmcnt(3)
	v_mfma_f32_32x32x16_bf16 v[48:63], v[234:237], v[84:87], v[48:63]
	ds_read_b128 v[84:87], v154 offset:17280
	s_waitcnt lgkmcnt(3)
	v_mfma_f32_32x32x16_bf16 v[16:31], v[234:237], v[88:91], v[16:31]
	ds_read_b128 v[88:91], v154 offset:34176
	s_waitcnt lgkmcnt(3)
	v_mfma_f32_32x32x16_bf16 v[0:15], v[234:237], v[92:95], v[0:15]
	ds_read_b128 v[92:95], v154 offset:51072
	s_waitcnt vmcnt(3) lgkmcnt(3)
	v_mfma_f32_32x32x16_bf16 v[64:79], v[238:241], v[80:83], v[64:79]
	ds_read_b128 v[80:83], v154 offset:416
	s_waitcnt lgkmcnt(3)
	v_mfma_f32_32x32x16_bf16 v[48:63], v[238:241], v[84:87], v[48:63]
	ds_read_b128 v[84:87], v154 offset:17312
	s_waitcnt lgkmcnt(3)
	v_mfma_f32_32x32x16_bf16 v[16:31], v[238:241], v[88:91], v[16:31]
	ds_read_b128 v[88:91], v154 offset:34208
	s_waitcnt lgkmcnt(3)
	v_mfma_f32_32x32x16_bf16 v[0:15], v[238:241], v[92:95], v[0:15]
	ds_read_b128 v[92:95], v154 offset:51104
	s_waitcnt vmcnt(2) lgkmcnt(3)
	v_mfma_f32_32x32x16_bf16 v[64:79], v[242:245], v[80:83], v[64:79]
	ds_read_b128 v[80:83], v154 offset:448
	s_waitcnt lgkmcnt(3)
	v_mfma_f32_32x32x16_bf16 v[48:63], v[242:245], v[84:87], v[48:63]
	ds_read_b128 v[84:87], v154 offset:17344
	s_waitcnt lgkmcnt(3)
	v_mfma_f32_32x32x16_bf16 v[16:31], v[242:245], v[88:91], v[16:31]
	ds_read_b128 v[88:91], v154 offset:34240
	s_waitcnt lgkmcnt(3)
	v_mfma_f32_32x32x16_bf16 v[0:15], v[242:245], v[92:95], v[0:15]
	ds_read_b128 v[92:95], v154 offset:51136
	s_waitcnt vmcnt(1) lgkmcnt(3)
	v_mfma_f32_32x32x16_bf16 v[64:79], v[246:249], v[80:83], v[64:79]
	ds_read_b128 v[80:83], v154 offset:480
	s_waitcnt lgkmcnt(3)
	v_mfma_f32_32x32x16_bf16 v[48:63], v[246:249], v[84:87], v[48:63]
	ds_read_b128 v[84:87], v154 offset:17376
	s_waitcnt lgkmcnt(3)
	v_mfma_f32_32x32x16_bf16 v[16:31], v[246:249], v[88:91], v[16:31]
	ds_read_b128 v[88:91], v154 offset:34272
	s_waitcnt lgkmcnt(3)
	v_mfma_f32_32x32x16_bf16 v[0:15], v[246:249], v[92:95], v[0:15]
	ds_read_b128 v[92:95], v154 offset:51168
	s_waitcnt vmcnt(0) lgkmcnt(3)
	v_mfma_f32_32x32x16_bf16 v[64:79], v[250:253], v[80:83], v[64:79]
	s_waitcnt lgkmcnt(2)
	v_mfma_f32_32x32x16_bf16 v[48:63], v[250:253], v[84:87], v[48:63]
	s_waitcnt lgkmcnt(1)
	v_mfma_f32_32x32x16_bf16 v[16:31], v[250:253], v[88:91], v[16:31]
	s_waitcnt lgkmcnt(0)
	v_mfma_f32_32x32x16_bf16 v[0:15], v[250:253], v[92:95], v[0:15]
.LBB0_724:
	v_lshl_add_u64 v[38:39], s[88:89], 1, v[152:153]
	global_load_dwordx4 v[100:103], v[38:39], off offset:-32
	global_load_dwordx4 v[104:107], v[38:39], off
	global_load_dwordx4 v[108:111], v[38:39], off offset:32
	global_load_dwordx4 v[166:169], v[38:39], off offset:64
	global_load_dwordx4 v[170:173], v[38:39], off offset:96
	global_load_dwordx4 v[174:177], v[38:39], off offset:128
	global_load_dwordx4 v[190:193], v[38:39], off offset:160
	global_load_dwordx4 v[194:197], v[38:39], off offset:192
	v_add_u32_e32 v32, 0x10800, v156
	s_waitcnt lgkmcnt(0)
	s_barrier
	ds_read_b128 v[198:201], v32
	ds_read_b128 v[202:205], v32 offset:16
	ds_read_b128 v[206:209], v32 offset:16896
	ds_read_b128 v[234:237], v32 offset:16912
	ds_read_b128 v[238:241], v32 offset:33792
	ds_read_b128 v[242:245], v32 offset:33808
	s_waitcnt vmcnt(7) lgkmcnt(4)
	v_cvt_pk_bf16_f32 v246, v198, v199
	v_cvt_pk_bf16_f32 v247, v200, v201
	v_cvt_pk_bf16_f32 v248, v202, v203
	v_cvt_pk_bf16_f32 v249, v204, v205
	s_nop 1
	v_mfma_f32_32x32x16_bf16 v[64:79], v[100:103], v[246:249], v[64:79]
	ds_read_b128 v[198:201], v32 offset:50688
	ds_read_b128 v[202:205], v32 offset:50704
	s_waitcnt lgkmcnt(4)
	v_cvt_pk_bf16_f32 v250, v206, v207
	v_cvt_pk_bf16_f32 v251, v208, v209
	v_cvt_pk_bf16_f32 v252, v234, v235
	v_cvt_pk_bf16_f32 v253, v236, v237
	s_nop 1
	v_mfma_f32_32x32x16_bf16 v[48:63], v[100:103], v[250:253], v[48:63]
	ds_read_b128 v[206:209], v32 offset:64
	ds_read_b128 v[234:237], v32 offset:80
	s_waitcnt lgkmcnt(4)
	v_cvt_pk_bf16_f32 v246, v238, v239
	v_cvt_pk_bf16_f32 v247, v240, v241
	v_cvt_pk_bf16_f32 v248, v242, v243
	v_cvt_pk_bf16_f32 v249, v244, v245
	s_nop 1
	v_mfma_f32_32x32x16_bf16 v[16:31], v[100:103], v[246:249], v[16:31]
	ds_read_b128 v[238:241], v32 offset:16960
	ds_read_b128 v[242:245], v32 offset:16976
	s_waitcnt lgkmcnt(4)
	v_cvt_pk_bf16_f32 v250, v198, v199
	v_cvt_pk_bf16_f32 v251, v200, v201
	v_cvt_pk_bf16_f32 v252, v202, v203
	v_cvt_pk_bf16_f32 v253, v204, v205
	s_nop 1
	v_mfma_f32_32x32x16_bf16 v[0:15], v[100:103], v[250:253], v[0:15]
	ds_read_b128 v[198:201], v32 offset:33856
	ds_read_b128 v[202:205], v32 offset:33872
	s_waitcnt vmcnt(6) lgkmcnt(4)
	v_cvt_pk_bf16_f32 v246, v206, v207
	v_cvt_pk_bf16_f32 v247, v208, v209
	v_cvt_pk_bf16_f32 v248, v234, v235
	v_cvt_pk_bf16_f32 v249, v236, v237
	s_nop 1
	v_mfma_f32_32x32x16_bf16 v[64:79], v[104:107], v[246:249], v[64:79]
	ds_read_b128 v[206:209], v32 offset:50752
	ds_read_b128 v[234:237], v32 offset:50768
	s_waitcnt lgkmcnt(4)
	v_cvt_pk_bf16_f32 v250, v238, v239
	v_cvt_pk_bf16_f32 v251, v240, v241
	v_cvt_pk_bf16_f32 v252, v242, v243
	v_cvt_pk_bf16_f32 v253, v244, v245
	s_nop 1
	v_mfma_f32_32x32x16_bf16 v[48:63], v[104:107], v[250:253], v[48:63]
	ds_read_b128 v[238:241], v32 offset:128
	ds_read_b128 v[242:245], v32 offset:144
	s_waitcnt lgkmcnt(4)
	v_cvt_pk_bf16_f32 v246, v198, v199
	v_cvt_pk_bf16_f32 v247, v200, v201
	v_cvt_pk_bf16_f32 v248, v202, v203
	v_cvt_pk_bf16_f32 v249, v204, v205
	s_nop 1
	v_mfma_f32_32x32x16_bf16 v[16:31], v[104:107], v[246:249], v[16:31]
	ds_read_b128 v[198:201], v32 offset:17024
	ds_read_b128 v[202:205], v32 offset:17040
	s_waitcnt lgkmcnt(4)
	v_cvt_pk_bf16_f32 v250, v206, v207
	v_cvt_pk_bf16_f32 v251, v208, v209
	v_cvt_pk_bf16_f32 v252, v234, v235
	v_cvt_pk_bf16_f32 v253, v236, v237
	s_nop 1
	v_mfma_f32_32x32x16_bf16 v[0:15], v[104:107], v[250:253], v[0:15]
	ds_read_b128 v[206:209], v32 offset:33920
	ds_read_b128 v[234:237], v32 offset:33936
	s_waitcnt vmcnt(5) lgkmcnt(4)
	v_cvt_pk_bf16_f32 v246, v238, v239
	v_cvt_pk_bf16_f32 v247, v240, v241
	v_cvt_pk_bf16_f32 v248, v242, v243
	v_cvt_pk_bf16_f32 v249, v244, v245
	s_nop 1
	v_mfma_f32_32x32x16_bf16 v[64:79], v[108:111], v[246:249], v[64:79]
	ds_read_b128 v[238:241], v32 offset:50816
	ds_read_b128 v[242:245], v32 offset:50832
	s_waitcnt lgkmcnt(4)
	v_cvt_pk_bf16_f32 v250, v198, v199
	v_cvt_pk_bf16_f32 v251, v200, v201
	v_cvt_pk_bf16_f32 v252, v202, v203
	v_cvt_pk_bf16_f32 v253, v204, v205
	s_nop 1
	v_mfma_f32_32x32x16_bf16 v[48:63], v[108:111], v[250:253], v[48:63]
	ds_read_b128 v[198:201], v32 offset:192
	ds_read_b128 v[202:205], v32 offset:208
	s_waitcnt lgkmcnt(4)
	v_cvt_pk_bf16_f32 v246, v206, v207
	v_cvt_pk_bf16_f32 v247, v208, v209
	v_cvt_pk_bf16_f32 v248, v234, v235
	v_cvt_pk_bf16_f32 v249, v236, v237
	s_nop 1
	v_mfma_f32_32x32x16_bf16 v[16:31], v[108:111], v[246:249], v[16:31]
	ds_read_b128 v[206:209], v32 offset:17088
	ds_read_b128 v[234:237], v32 offset:17104
	s_waitcnt lgkmcnt(4)
	v_cvt_pk_bf16_f32 v250, v238, v239
	v_cvt_pk_bf16_f32 v251, v240, v241
	v_cvt_pk_bf16_f32 v252, v242, v243
	v_cvt_pk_bf16_f32 v253, v244, v245
	s_nop 1
	v_mfma_f32_32x32x16_bf16 v[0:15], v[108:111], v[250:253], v[0:15]
	ds_read_b128 v[238:241], v32 offset:33984
	ds_read_b128 v[242:245], v32 offset:34000
	s_waitcnt vmcnt(4) lgkmcnt(4)
	v_cvt_pk_bf16_f32 v246, v198, v199
	v_cvt_pk_bf16_f32 v247, v200, v201
	v_cvt_pk_bf16_f32 v248, v202, v203
	v_cvt_pk_bf16_f32 v249, v204, v205
	s_nop 1
	v_mfma_f32_32x32x16_bf16 v[64:79], v[166:169], v[246:249], v[64:79]
	ds_read_b128 v[198:201], v32 offset:50880
	ds_read_b128 v[202:205], v32 offset:50896
	s_waitcnt lgkmcnt(4)
	v_cvt_pk_bf16_f32 v250, v206, v207
	v_cvt_pk_bf16_f32 v251, v208, v209
	v_cvt_pk_bf16_f32 v252, v234, v235
	v_cvt_pk_bf16_f32 v253, v236, v237
	s_nop 1
	v_mfma_f32_32x32x16_bf16 v[48:63], v[166:169], v[250:253], v[48:63]
	ds_read_b128 v[206:209], v32 offset:256
	ds_read_b128 v[234:237], v32 offset:272
	s_waitcnt lgkmcnt(4)
	v_cvt_pk_bf16_f32 v246, v238, v239
	v_cvt_pk_bf16_f32 v247, v240, v241
	v_cvt_pk_bf16_f32 v248, v242, v243
	v_cvt_pk_bf16_f32 v249, v244, v245
	s_nop 1
	v_mfma_f32_32x32x16_bf16 v[16:31], v[166:169], v[246:249], v[16:31]
	ds_read_b128 v[238:241], v32 offset:17152
	ds_read_b128 v[242:245], v32 offset:17168
	s_waitcnt lgkmcnt(4)
	v_cvt_pk_bf16_f32 v250, v198, v199
	v_cvt_pk_bf16_f32 v251, v200, v201
	v_cvt_pk_bf16_f32 v252, v202, v203
	v_cvt_pk_bf16_f32 v253, v204, v205
	s_nop 1
	v_mfma_f32_32x32x16_bf16 v[0:15], v[166:169], v[250:253], v[0:15]
	ds_read_b128 v[198:201], v32 offset:34048
	ds_read_b128 v[202:205], v32 offset:34064
	s_waitcnt vmcnt(3) lgkmcnt(4)
	v_cvt_pk_bf16_f32 v246, v206, v207
	v_cvt_pk_bf16_f32 v247, v208, v209
	v_cvt_pk_bf16_f32 v248, v234, v235
	v_cvt_pk_bf16_f32 v249, v236, v237
	s_nop 1
	v_mfma_f32_32x32x16_bf16 v[64:79], v[170:173], v[246:249], v[64:79]
	ds_read_b128 v[206:209], v32 offset:50944
	ds_read_b128 v[234:237], v32 offset:50960
	s_waitcnt lgkmcnt(4)
	v_cvt_pk_bf16_f32 v250, v238, v239
	v_cvt_pk_bf16_f32 v251, v240, v241
	v_cvt_pk_bf16_f32 v252, v242, v243
	v_cvt_pk_bf16_f32 v253, v244, v245
	s_nop 1
	v_mfma_f32_32x32x16_bf16 v[48:63], v[170:173], v[250:253], v[48:63]
	ds_read_b128 v[238:241], v32 offset:320
	ds_read_b128 v[242:245], v32 offset:336
	s_waitcnt lgkmcnt(4)
	v_cvt_pk_bf16_f32 v246, v198, v199
	v_cvt_pk_bf16_f32 v247, v200, v201
	v_cvt_pk_bf16_f32 v248, v202, v203
	v_cvt_pk_bf16_f32 v249, v204, v205
	s_nop 1
	v_mfma_f32_32x32x16_bf16 v[16:31], v[170:173], v[246:249], v[16:31]
	ds_read_b128 v[198:201], v32 offset:17216
	ds_read_b128 v[202:205], v32 offset:17232
	s_waitcnt lgkmcnt(4)
	v_cvt_pk_bf16_f32 v250, v206, v207
	v_cvt_pk_bf16_f32 v251, v208, v209
	v_cvt_pk_bf16_f32 v252, v234, v235
	v_cvt_pk_bf16_f32 v253, v236, v237
	s_nop 1
	v_mfma_f32_32x32x16_bf16 v[0:15], v[170:173], v[250:253], v[0:15]
	ds_read_b128 v[206:209], v32 offset:34112
	ds_read_b128 v[234:237], v32 offset:34128
	s_waitcnt vmcnt(2) lgkmcnt(4)
	v_cvt_pk_bf16_f32 v246, v238, v239
	v_cvt_pk_bf16_f32 v247, v240, v241
	v_cvt_pk_bf16_f32 v248, v242, v243
	v_cvt_pk_bf16_f32 v249, v244, v245
	s_nop 1
	v_mfma_f32_32x32x16_bf16 v[64:79], v[174:177], v[246:249], v[64:79]
	ds_read_b128 v[238:241], v32 offset:51008
	ds_read_b128 v[242:245], v32 offset:51024
	s_waitcnt lgkmcnt(4)
	v_cvt_pk_bf16_f32 v250, v198, v199
	v_cvt_pk_bf16_f32 v251, v200, v201
	v_cvt_pk_bf16_f32 v252, v202, v203
	v_cvt_pk_bf16_f32 v253, v204, v205
	s_nop 1
	v_mfma_f32_32x32x16_bf16 v[48:63], v[174:177], v[250:253], v[48:63]
	ds_read_b128 v[198:201], v32 offset:384
	ds_read_b128 v[202:205], v32 offset:400
	s_waitcnt lgkmcnt(4)
	v_cvt_pk_bf16_f32 v246, v206, v207
	v_cvt_pk_bf16_f32 v247, v208, v209
	v_cvt_pk_bf16_f32 v248, v234, v235
	v_cvt_pk_bf16_f32 v249, v236, v237
	s_nop 1
	v_mfma_f32_32x32x16_bf16 v[16:31], v[174:177], v[246:249], v[16:31]
	ds_read_b128 v[206:209], v32 offset:17280
	ds_read_b128 v[234:237], v32 offset:17296
	s_waitcnt lgkmcnt(4)
	v_cvt_pk_bf16_f32 v250, v238, v239
	v_cvt_pk_bf16_f32 v251, v240, v241
	v_cvt_pk_bf16_f32 v252, v242, v243
	v_cvt_pk_bf16_f32 v253, v244, v245
	s_nop 1
	v_mfma_f32_32x32x16_bf16 v[0:15], v[174:177], v[250:253], v[0:15]
	ds_read_b128 v[238:241], v32 offset:34176
	ds_read_b128 v[242:245], v32 offset:34192
	s_waitcnt vmcnt(1) lgkmcnt(4)
	v_cvt_pk_bf16_f32 v246, v198, v199
	v_cvt_pk_bf16_f32 v247, v200, v201
	v_cvt_pk_bf16_f32 v248, v202, v203
	v_cvt_pk_bf16_f32 v249, v204, v205
	s_nop 1
	v_mfma_f32_32x32x16_bf16 v[64:79], v[190:193], v[246:249], v[64:79]
	ds_read_b128 v[198:201], v32 offset:51072
	ds_read_b128 v[202:205], v32 offset:51088
	s_waitcnt lgkmcnt(4)
	v_cvt_pk_bf16_f32 v250, v206, v207
	v_cvt_pk_bf16_f32 v251, v208, v209
	v_cvt_pk_bf16_f32 v252, v234, v235
	v_cvt_pk_bf16_f32 v253, v236, v237
	s_nop 1
	v_mfma_f32_32x32x16_bf16 v[48:63], v[190:193], v[250:253], v[48:63]
	ds_read_b128 v[206:209], v32 offset:448
	ds_read_b128 v[234:237], v32 offset:464
	s_waitcnt lgkmcnt(4)
	v_cvt_pk_bf16_f32 v246, v238, v239
	v_cvt_pk_bf16_f32 v247, v240, v241
	v_cvt_pk_bf16_f32 v248, v242, v243
	v_cvt_pk_bf16_f32 v249, v244, v245
	s_nop 1
	v_mfma_f32_32x32x16_bf16 v[16:31], v[190:193], v[246:249], v[16:31]
	ds_read_b128 v[238:241], v32 offset:17344
	ds_read_b128 v[242:245], v32 offset:17360
	s_waitcnt lgkmcnt(4)
	v_cvt_pk_bf16_f32 v250, v198, v199
	v_cvt_pk_bf16_f32 v251, v200, v201
	v_cvt_pk_bf16_f32 v252, v202, v203
	v_cvt_pk_bf16_f32 v253, v204, v205
	s_nop 1
	v_mfma_f32_32x32x16_bf16 v[0:15], v[190:193], v[250:253], v[0:15]
	ds_read_b128 v[198:201], v32 offset:34240
	ds_read_b128 v[202:205], v32 offset:34256
	s_waitcnt vmcnt(0) lgkmcnt(4)
	v_cvt_pk_bf16_f32 v246, v206, v207
	v_cvt_pk_bf16_f32 v247, v208, v209
	v_cvt_pk_bf16_f32 v248, v234, v235
	v_cvt_pk_bf16_f32 v249, v236, v237
	s_nop 1
	v_mfma_f32_32x32x16_bf16 v[64:79], v[194:197], v[246:249], v[64:79]
	ds_read_b128 v[206:209], v32 offset:51136
	ds_read_b128 v[234:237], v32 offset:51152
	s_waitcnt lgkmcnt(4)
	v_cvt_pk_bf16_f32 v250, v238, v239
	v_cvt_pk_bf16_f32 v251, v240, v241
	v_cvt_pk_bf16_f32 v252, v242, v243
	v_cvt_pk_bf16_f32 v253, v244, v245
	s_nop 1
	v_mfma_f32_32x32x16_bf16 v[48:63], v[194:197], v[250:253], v[48:63]
	s_waitcnt lgkmcnt(2)
	v_cvt_pk_bf16_f32 v246, v198, v199
	v_cvt_pk_bf16_f32 v247, v200, v201
	v_cvt_pk_bf16_f32 v248, v202, v203
	v_cvt_pk_bf16_f32 v249, v204, v205
	s_nop 1
	v_mfma_f32_32x32x16_bf16 v[16:31], v[194:197], v[246:249], v[16:31]
	s_waitcnt lgkmcnt(0)
	v_cvt_pk_bf16_f32 v250, v206, v207
	v_cvt_pk_bf16_f32 v251, v208, v209
	v_cvt_pk_bf16_f32 v252, v234, v235
	v_cvt_pk_bf16_f32 v253, v236, v237
	s_nop 1
	v_mfma_f32_32x32x16_bf16 v[0:15], v[194:197], v[250:253], v[0:15]
	s_movk_i32 s88, 0x80
	s_mov_b64 s[10:11], 0
	s_and_b64 vcc, exec, s[8:9]
	s_barrier
	s_cbranch_vccz .LBB0_719
	v_mul_f32_e32 v32, 0x3d372713, v64
	v_mul_f32_e32 v32, v64, v32
	v_fma_f32 v32, v64, v32, v64
	v_mul_f32_e32 v32, 0x3f4c422a, v32
	v_add_f32_e32 v32, v32, v32
	v_mul_f32_e32 v32, 0x3fb8aa3b, v32
	v_exp_f32_e32 v32, v32
	v_mul_f32_e32 v38, 0.5, v64
	v_mul_f32_e32 v39, 0.5, v65
	v_mul_f32_e32 v40, 0.5, v67
	v_add_f32_e32 v32, 1.0, v32
	v_rcp_f32_e32 v32, v32
	s_ashr_i32 s8, s6, 5
	s_ashr_i32 s9, s8, 31
	s_lshl_b64 s[10:11], s[8:9], 11
	v_fma_f32 v32, v32, -2.0, 1.0
	v_add_f32_e32 v32, 1.0, v32
	v_mul_f32_e32 v32, v38, v32
	v_mul_f32_e32 v38, 0x3d372713, v65
	v_mul_f32_e32 v38, v65, v38
	v_fma_f32 v38, v65, v38, v65
	v_mul_f32_e32 v38, 0x3f4c422a, v38
	v_add_f32_e32 v38, v38, v38
	v_mul_f32_e32 v38, 0x3fb8aa3b, v38
	v_exp_f32_e32 v38, v38
	s_lshl_b32 s7, s23, 5
	v_mov_b32_e32 v35, s11
	v_or_b32_e32 v34, s10, v118
	v_add_f32_e32 v38, 1.0, v38
	v_rcp_f32_e32 v38, v38
	s_add_u32 s8, s14, s7
	v_lshl_add_u64 v[36:37], v[34:35], 0, v[114:115]
	s_addc_u32 s9, s15, 0
	v_fma_f32 v38, v38, -2.0, 1.0
	v_add_f32_e32 v38, 1.0, v38
	v_mul_f32_e32 v38, v39, v38
	v_cvt_pk_bf16_f32 v38, v32, v38
	v_mul_f32_e32 v32, 0x3d372713, v66
	v_mul_f32_e32 v32, v66, v32
	v_fma_f32 v32, v66, v32, v66
	v_mul_f32_e32 v32, 0x3f4c422a, v32
	v_add_f32_e32 v32, v32, v32
	v_mul_f32_e32 v32, 0x3fb8aa3b, v32
	v_exp_f32_e32 v32, v32
	v_mul_f32_e32 v39, 0.5, v66
	v_lshlrev_b64 v[36:37], 10, v[36:37]
	v_lshl_add_u64 v[36:37], s[8:9], 0, v[36:37]
	v_add_f32_e32 v32, 1.0, v32
	v_rcp_f32_e32 v32, v32
	v_mov_b32_e32 v147, v33
	v_lshl_add_u64 v[36:37], v[36:37], 0, v[146:147]
	v_lshl_add_u64 v[34:35], v[34:35], 0, v[136:137]
	v_fma_f32 v32, v32, -2.0, 1.0
	v_add_f32_e32 v32, 1.0, v32
	v_mul_f32_e32 v32, v39, v32
	v_mul_f32_e32 v39, 0x3d372713, v67
	v_mul_f32_e32 v39, v67, v39
	v_fma_f32 v39, v67, v39, v67
	v_mul_f32_e32 v39, 0x3f4c422a, v39
	v_add_f32_e32 v39, v39, v39
	v_mul_f32_e32 v39, 0x3fb8aa3b, v39
	v_exp_f32_e32 v39, v39
	v_lshlrev_b64 v[34:35], 10, v[34:35]
	v_lshl_add_u64 v[34:35], s[8:9], 0, v[34:35]
	v_lshl_add_u64 v[34:35], v[34:35], 0, v[146:147]
	v_add_f32_e32 v39, 1.0, v39
	v_rcp_f32_e32 v39, v39
	s_add_i32 s6, s6, s28
	s_add_i32 s17, s17, s28
	s_cmpk_gt_i32 s6, 0x1ff
	v_fma_f32 v39, v39, -2.0, 1.0
	v_add_f32_e32 v39, 1.0, v39
	v_mul_f32_e32 v39, v40, v39
	v_cvt_pk_bf16_f32 v39, v32, v39
	v_mul_f32_e32 v32, 0x3d372713, v68
	v_mul_f32_e32 v32, v68, v32
	v_fma_f32 v32, v68, v32, v68
	v_mul_f32_e32 v32, 0x3f4c422a, v32
	v_add_f32_e32 v32, v32, v32
	v_mul_f32_e32 v32, 0x3fb8aa3b, v32
	v_exp_f32_e32 v32, v32
	global_store_dwordx2 v[36:37], v[38:39], off
	v_mul_f32_e32 v38, 0.5, v68
	v_mul_f32_e32 v39, 0.5, v69
	v_add_f32_e32 v32, 1.0, v32
	v_rcp_f32_e32 v32, v32
	v_mul_f32_e32 v40, 0.5, v71
	v_fma_f32 v32, v32, -2.0, 1.0
	v_add_f32_e32 v32, 1.0, v32
	v_mul_f32_e32 v32, v38, v32
	v_mul_f32_e32 v38, 0x3d372713, v69
	v_mul_f32_e32 v38, v69, v38
	v_fma_f32 v38, v69, v38, v69
	v_mul_f32_e32 v38, 0x3f4c422a, v38
	v_add_f32_e32 v38, v38, v38
	v_mul_f32_e32 v38, 0x3fb8aa3b, v38
	v_exp_f32_e32 v38, v38
	s_nop 0
	v_add_f32_e32 v38, 1.0, v38
	v_rcp_f32_e32 v38, v38
	s_nop 0
	v_fma_f32 v38, v38, -2.0, 1.0
	v_add_f32_e32 v38, 1.0, v38
	v_mul_f32_e32 v38, v39, v38
	v_cvt_pk_bf16_f32 v38, v32, v38
	v_mul_f32_e32 v32, 0x3d372713, v70
	v_mul_f32_e32 v32, v70, v32
	v_fma_f32 v32, v70, v32, v70
	v_mul_f32_e32 v32, 0x3f4c422a, v32
	v_add_f32_e32 v32, v32, v32
	v_mul_f32_e32 v32, 0x3fb8aa3b, v32
	v_exp_f32_e32 v32, v32
	v_mul_f32_e32 v39, 0.5, v70
	v_add_f32_e32 v32, 1.0, v32
	v_rcp_f32_e32 v32, v32
	s_nop 0
	v_fma_f32 v32, v32, -2.0, 1.0
	v_add_f32_e32 v32, 1.0, v32
	v_mul_f32_e32 v32, v39, v32
	v_mul_f32_e32 v39, 0x3d372713, v71
	v_mul_f32_e32 v39, v71, v39
	v_fma_f32 v39, v71, v39, v71
	v_mul_f32_e32 v39, 0x3f4c422a, v39
	v_add_f32_e32 v39, v39, v39
	v_mul_f32_e32 v39, 0x3fb8aa3b, v39
	v_exp_f32_e32 v39, v39
	s_nop 0
	v_add_f32_e32 v39, 1.0, v39
	v_rcp_f32_e32 v39, v39
	s_nop 0
	v_fma_f32 v39, v39, -2.0, 1.0
	v_add_f32_e32 v39, 1.0, v39
	v_mul_f32_e32 v39, v40, v39
	v_cvt_pk_bf16_f32 v39, v32, v39
	v_mul_f32_e32 v32, 0x3d372713, v72
	v_mul_f32_e32 v32, v72, v32
	v_fma_f32 v32, v72, v32, v72
	v_mul_f32_e32 v32, 0x3f4c422a, v32
	v_add_f32_e32 v32, v32, v32
	v_mul_f32_e32 v32, 0x3fb8aa3b, v32
	v_exp_f32_e32 v32, v32
	global_store_dwordx2 v[36:37], v[38:39], off offset:16
	v_mul_f32_e32 v36, 0.5, v72
	v_mul_f32_e32 v37, 0.5, v73
	v_add_f32_e32 v32, 1.0, v32
	v_rcp_f32_e32 v32, v32
	v_mul_f32_e32 v38, 0.5, v75
	v_mul_f32_e32 v39, 0.5, v49
	v_mul_f32_e32 v40, 0.5, v51
	v_fma_f32 v32, v32, -2.0, 1.0
	v_add_f32_e32 v32, 1.0, v32
	v_mul_f32_e32 v32, v36, v32
	v_mul_f32_e32 v36, 0x3d372713, v73
	v_mul_f32_e32 v36, v73, v36
	v_fma_f32 v36, v73, v36, v73
	v_mul_f32_e32 v36, 0x3f4c422a, v36
	v_add_f32_e32 v36, v36, v36
	v_mul_f32_e32 v36, 0x3fb8aa3b, v36
	v_exp_f32_e32 v36, v36
	s_nop 0
	v_add_f32_e32 v36, 1.0, v36
	v_rcp_f32_e32 v36, v36
	s_nop 0
	v_fma_f32 v36, v36, -2.0, 1.0
	v_add_f32_e32 v36, 1.0, v36
	v_mul_f32_e32 v36, v37, v36
	v_cvt_pk_bf16_f32 v36, v32, v36
	v_mul_f32_e32 v32, 0x3d372713, v74
	v_mul_f32_e32 v32, v74, v32
	v_fma_f32 v32, v74, v32, v74
	v_mul_f32_e32 v32, 0x3f4c422a, v32
	v_add_f32_e32 v32, v32, v32
	v_mul_f32_e32 v32, 0x3fb8aa3b, v32
	v_exp_f32_e32 v32, v32
	v_mul_f32_e32 v37, 0.5, v74
	v_add_f32_e32 v32, 1.0, v32
	v_rcp_f32_e32 v32, v32
	s_nop 0
	v_fma_f32 v32, v32, -2.0, 1.0
	v_add_f32_e32 v32, 1.0, v32
	v_mul_f32_e32 v32, v37, v32
	v_mul_f32_e32 v37, 0x3d372713, v75
	v_mul_f32_e32 v37, v75, v37
	v_fma_f32 v37, v75, v37, v75
	v_mul_f32_e32 v37, 0x3f4c422a, v37
	v_add_f32_e32 v37, v37, v37
	v_mul_f32_e32 v37, 0x3fb8aa3b, v37
	v_exp_f32_e32 v37, v37
	s_nop 0
	v_add_f32_e32 v37, 1.0, v37
	v_rcp_f32_e32 v37, v37
	s_nop 0
	v_fma_f32 v37, v37, -2.0, 1.0
	v_add_f32_e32 v37, 1.0, v37
	v_mul_f32_e32 v37, v38, v37
	v_cvt_pk_bf16_f32 v37, v32, v37
	v_mul_f32_e32 v32, 0x3d372713, v76
	v_mul_f32_e32 v32, v76, v32
	v_fma_f32 v32, v76, v32, v76
	v_mul_f32_e32 v32, 0x3f4c422a, v32
	v_add_f32_e32 v32, v32, v32
	v_mul_f32_e32 v32, 0x3fb8aa3b, v32
	v_exp_f32_e32 v32, v32
	global_store_dwordx2 v[34:35], v[36:37], off
	v_mul_f32_e32 v36, 0.5, v76
	v_mul_f32_e32 v37, 0.5, v77
	v_add_f32_e32 v32, 1.0, v32
	v_rcp_f32_e32 v32, v32
	v_mul_f32_e32 v38, 0.5, v79
	v_fma_f32 v32, v32, -2.0, 1.0
	v_add_f32_e32 v32, 1.0, v32
	v_mul_f32_e32 v32, v36, v32
	v_mul_f32_e32 v36, 0x3d372713, v77
	v_mul_f32_e32 v36, v77, v36
	v_fma_f32 v36, v77, v36, v77
	v_mul_f32_e32 v36, 0x3f4c422a, v36
	v_add_f32_e32 v36, v36, v36
	v_mul_f32_e32 v36, 0x3fb8aa3b, v36
	v_exp_f32_e32 v36, v36
	s_nop 0
	v_add_f32_e32 v36, 1.0, v36
	v_rcp_f32_e32 v36, v36
	s_nop 0
	v_fma_f32 v36, v36, -2.0, 1.0
	v_add_f32_e32 v36, 1.0, v36
	v_mul_f32_e32 v36, v37, v36
	v_cvt_pk_bf16_f32 v36, v32, v36
	v_mul_f32_e32 v32, 0x3d372713, v78
	v_mul_f32_e32 v32, v78, v32
	v_fma_f32 v32, v78, v32, v78
	v_mul_f32_e32 v32, 0x3f4c422a, v32
	v_add_f32_e32 v32, v32, v32
	v_mul_f32_e32 v32, 0x3fb8aa3b, v32
	v_exp_f32_e32 v32, v32
	v_mul_f32_e32 v37, 0.5, v78
	v_add_f32_e32 v32, 1.0, v32
	v_rcp_f32_e32 v32, v32
	s_nop 0
	v_fma_f32 v32, v32, -2.0, 1.0
	v_add_f32_e32 v32, 1.0, v32
	v_mul_f32_e32 v32, v37, v32
	v_mul_f32_e32 v37, 0x3d372713, v79
	v_mul_f32_e32 v37, v79, v37
	v_fma_f32 v37, v79, v37, v79
	v_mul_f32_e32 v37, 0x3f4c422a, v37
	v_add_f32_e32 v37, v37, v37
	v_mul_f32_e32 v37, 0x3fb8aa3b, v37
	v_exp_f32_e32 v37, v37
	s_nop 0
	v_add_f32_e32 v37, 1.0, v37
	v_rcp_f32_e32 v37, v37
	s_nop 0
	v_fma_f32 v37, v37, -2.0, 1.0
	v_add_f32_e32 v37, 1.0, v37
	v_mul_f32_e32 v37, v38, v37
	v_cvt_pk_bf16_f32 v37, v32, v37
	v_mul_f32_e32 v32, 0x3d372713, v48
	v_mul_f32_e32 v32, v48, v32
	v_fma_f32 v32, v48, v32, v48
	v_mul_f32_e32 v32, 0x3f4c422a, v32
	v_add_f32_e32 v32, v32, v32
	v_mul_f32_e32 v32, 0x3fb8aa3b, v32
	v_exp_f32_e32 v32, v32
	v_mul_f32_e32 v38, 0.5, v48
	global_store_dwordx2 v[34:35], v[36:37], off offset:16
	v_mov_b32_e32 v35, s11
	v_add_f32_e32 v32, 1.0, v32
	v_rcp_f32_e32 v32, v32
	v_or_b32_e32 v34, s10, v138
	v_lshl_add_u64 v[36:37], v[34:35], 0, v[114:115]
	v_lshlrev_b64 v[36:37], 10, v[36:37]
	v_fma_f32 v32, v32, -2.0, 1.0
	v_add_f32_e32 v32, 1.0, v32
	v_mul_f32_e32 v32, v38, v32
	v_mul_f32_e32 v38, 0x3d372713, v49
	v_mul_f32_e32 v38, v49, v38
	v_fma_f32 v38, v49, v38, v49
	v_mul_f32_e32 v38, 0x3f4c422a, v38
	v_add_f32_e32 v38, v38, v38
	v_mul_f32_e32 v38, 0x3fb8aa3b, v38
	v_exp_f32_e32 v38, v38
	v_lshl_add_u64 v[36:37], s[8:9], 0, v[36:37]
	v_lshl_add_u64 v[36:37], v[36:37], 0, v[146:147]
	v_lshl_add_u64 v[34:35], v[34:35], 0, v[136:137]
	v_add_f32_e32 v38, 1.0, v38
	v_rcp_f32_e32 v38, v38
	v_lshlrev_b64 v[34:35], 10, v[34:35]
	v_lshl_add_u64 v[34:35], s[8:9], 0, v[34:35]
	v_lshl_add_u64 v[34:35], v[34:35], 0, v[146:147]
	v_fma_f32 v38, v38, -2.0, 1.0
	v_add_f32_e32 v38, 1.0, v38
	v_mul_f32_e32 v38, v39, v38
	v_cvt_pk_bf16_f32 v38, v32, v38
	v_mul_f32_e32 v32, 0x3d372713, v50
	v_mul_f32_e32 v32, v50, v32
	v_fma_f32 v32, v50, v32, v50
	v_mul_f32_e32 v32, 0x3f4c422a, v32
	v_add_f32_e32 v32, v32, v32
	v_mul_f32_e32 v32, 0x3fb8aa3b, v32
	v_exp_f32_e32 v32, v32
	v_mul_f32_e32 v39, 0.5, v50
	v_add_f32_e32 v32, 1.0, v32
	v_rcp_f32_e32 v32, v32
	s_nop 0
	v_fma_f32 v32, v32, -2.0, 1.0
	v_add_f32_e32 v32, 1.0, v32
	v_mul_f32_e32 v32, v39, v32
	v_mul_f32_e32 v39, 0x3d372713, v51
	v_mul_f32_e32 v39, v51, v39
	v_fma_f32 v39, v51, v39, v51
	v_mul_f32_e32 v39, 0x3f4c422a, v39
	v_add_f32_e32 v39, v39, v39
	v_mul_f32_e32 v39, 0x3fb8aa3b, v39
	v_exp_f32_e32 v39, v39
	s_nop 0
	v_add_f32_e32 v39, 1.0, v39
	v_rcp_f32_e32 v39, v39
	s_nop 0
	v_fma_f32 v39, v39, -2.0, 1.0
	v_add_f32_e32 v39, 1.0, v39
	v_mul_f32_e32 v39, v40, v39
	v_cvt_pk_bf16_f32 v39, v32, v39
	v_mul_f32_e32 v32, 0x3d372713, v52
	v_mul_f32_e32 v32, v52, v32
	v_fma_f32 v32, v52, v32, v52
	v_mul_f32_e32 v32, 0x3f4c422a, v32
	v_add_f32_e32 v32, v32, v32
	v_mul_f32_e32 v32, 0x3fb8aa3b, v32
	v_exp_f32_e32 v32, v32
	global_store_dwordx2 v[36:37], v[38:39], off
	v_mul_f32_e32 v38, 0.5, v52
	v_mul_f32_e32 v39, 0.5, v53
	v_add_f32_e32 v32, 1.0, v32
	v_rcp_f32_e32 v32, v32
	v_mul_f32_e32 v40, 0.5, v55
	v_fma_f32 v32, v32, -2.0, 1.0
	v_add_f32_e32 v32, 1.0, v32
	v_mul_f32_e32 v32, v38, v32
	v_mul_f32_e32 v38, 0x3d372713, v53
	v_mul_f32_e32 v38, v53, v38
	v_fma_f32 v38, v53, v38, v53
	v_mul_f32_e32 v38, 0x3f4c422a, v38
	v_add_f32_e32 v38, v38, v38
	v_mul_f32_e32 v38, 0x3fb8aa3b, v38
	v_exp_f32_e32 v38, v38
	s_nop 0
	v_add_f32_e32 v38, 1.0, v38
	v_rcp_f32_e32 v38, v38
	s_nop 0
	v_fma_f32 v38, v38, -2.0, 1.0
	v_add_f32_e32 v38, 1.0, v38
	v_mul_f32_e32 v38, v39, v38
	v_cvt_pk_bf16_f32 v38, v32, v38
	v_mul_f32_e32 v32, 0x3d372713, v54
	v_mul_f32_e32 v32, v54, v32
	v_fma_f32 v32, v54, v32, v54
	v_mul_f32_e32 v32, 0x3f4c422a, v32
	v_add_f32_e32 v32, v32, v32
	v_mul_f32_e32 v32, 0x3fb8aa3b, v32
	v_exp_f32_e32 v32, v32
	v_mul_f32_e32 v39, 0.5, v54
	v_add_f32_e32 v32, 1.0, v32
	v_rcp_f32_e32 v32, v32
	s_nop 0
	v_fma_f32 v32, v32, -2.0, 1.0
	v_add_f32_e32 v32, 1.0, v32
	v_mul_f32_e32 v32, v39, v32
	v_mul_f32_e32 v39, 0x3d372713, v55
	v_mul_f32_e32 v39, v55, v39
	v_fma_f32 v39, v55, v39, v55
	v_mul_f32_e32 v39, 0x3f4c422a, v39
	v_add_f32_e32 v39, v39, v39
	v_mul_f32_e32 v39, 0x3fb8aa3b, v39
	v_exp_f32_e32 v39, v39
	s_nop 0
	v_add_f32_e32 v39, 1.0, v39
	v_rcp_f32_e32 v39, v39
	s_nop 0
	v_fma_f32 v39, v39, -2.0, 1.0
	v_add_f32_e32 v39, 1.0, v39
	v_mul_f32_e32 v39, v40, v39
	v_cvt_pk_bf16_f32 v39, v32, v39
	v_mul_f32_e32 v32, 0x3d372713, v56
	v_mul_f32_e32 v32, v56, v32
	v_fma_f32 v32, v56, v32, v56
	v_mul_f32_e32 v32, 0x3f4c422a, v32
	v_add_f32_e32 v32, v32, v32
	v_mul_f32_e32 v32, 0x3fb8aa3b, v32
	v_exp_f32_e32 v32, v32
	global_store_dwordx2 v[36:37], v[38:39], off offset:16
	v_mul_f32_e32 v36, 0.5, v56
	v_mul_f32_e32 v37, 0.5, v57
	v_add_f32_e32 v32, 1.0, v32
	v_rcp_f32_e32 v32, v32
	v_mul_f32_e32 v38, 0.5, v59
	v_fma_f32 v32, v32, -2.0, 1.0
	v_add_f32_e32 v32, 1.0, v32
	v_mul_f32_e32 v32, v36, v32
	v_mul_f32_e32 v36, 0x3d372713, v57
	v_mul_f32_e32 v36, v57, v36
	v_fma_f32 v36, v57, v36, v57
	v_mul_f32_e32 v36, 0x3f4c422a, v36
	v_add_f32_e32 v36, v36, v36
	v_mul_f32_e32 v36, 0x3fb8aa3b, v36
	v_exp_f32_e32 v36, v36
	s_nop 0
	v_add_f32_e32 v36, 1.0, v36
	v_rcp_f32_e32 v36, v36
	s_nop 0
	v_fma_f32 v36, v36, -2.0, 1.0
	v_add_f32_e32 v36, 1.0, v36
	v_mul_f32_e32 v36, v37, v36
	v_cvt_pk_bf16_f32 v36, v32, v36
	v_mul_f32_e32 v32, 0x3d372713, v58
	v_mul_f32_e32 v32, v58, v32
	v_fma_f32 v32, v58, v32, v58
	v_mul_f32_e32 v32, 0x3f4c422a, v32
	v_add_f32_e32 v32, v32, v32
	v_mul_f32_e32 v32, 0x3fb8aa3b, v32
	v_exp_f32_e32 v32, v32
	v_mul_f32_e32 v37, 0.5, v58
	v_add_f32_e32 v32, 1.0, v32
	v_rcp_f32_e32 v32, v32
	s_nop 0
	v_fma_f32 v32, v32, -2.0, 1.0
	v_add_f32_e32 v32, 1.0, v32
	v_mul_f32_e32 v32, v37, v32
	v_mul_f32_e32 v37, 0x3d372713, v59
	v_mul_f32_e32 v37, v59, v37
	v_fma_f32 v37, v59, v37, v59
	v_mul_f32_e32 v37, 0x3f4c422a, v37
	v_add_f32_e32 v37, v37, v37
	v_mul_f32_e32 v37, 0x3fb8aa3b, v37
	v_exp_f32_e32 v37, v37
	s_nop 0
	v_add_f32_e32 v37, 1.0, v37
	v_rcp_f32_e32 v37, v37
	s_nop 0
	v_fma_f32 v37, v37, -2.0, 1.0
	v_add_f32_e32 v37, 1.0, v37
	v_mul_f32_e32 v37, v38, v37
	v_cvt_pk_bf16_f32 v37, v32, v37
	v_mul_f32_e32 v32, 0x3d372713, v60
	v_mul_f32_e32 v32, v60, v32
	v_fma_f32 v32, v60, v32, v60
	v_mul_f32_e32 v32, 0x3f4c422a, v32
	v_add_f32_e32 v32, v32, v32
	v_mul_f32_e32 v32, 0x3fb8aa3b, v32
	v_exp_f32_e32 v32, v32
	global_store_dwordx2 v[34:35], v[36:37], off
	v_mul_f32_e32 v36, 0.5, v60
	v_mul_f32_e32 v37, 0.5, v61
	v_add_f32_e32 v32, 1.0, v32
	v_rcp_f32_e32 v32, v32
	v_mul_f32_e32 v38, 0.5, v63
	v_fma_f32 v32, v32, -2.0, 1.0
	v_add_f32_e32 v32, 1.0, v32
	v_mul_f32_e32 v32, v36, v32
	v_mul_f32_e32 v36, 0x3d372713, v61
	v_mul_f32_e32 v36, v61, v36
	v_fma_f32 v36, v61, v36, v61
	v_mul_f32_e32 v36, 0x3f4c422a, v36
	v_add_f32_e32 v36, v36, v36
	v_mul_f32_e32 v36, 0x3fb8aa3b, v36
	v_exp_f32_e32 v36, v36
	s_nop 0
	v_add_f32_e32 v36, 1.0, v36
	v_rcp_f32_e32 v36, v36
	s_nop 0
	v_fma_f32 v36, v36, -2.0, 1.0
	v_add_f32_e32 v36, 1.0, v36
	v_mul_f32_e32 v36, v37, v36
	v_cvt_pk_bf16_f32 v36, v32, v36
	v_mul_f32_e32 v32, 0x3d372713, v62
	v_mul_f32_e32 v32, v62, v32
	v_fma_f32 v32, v62, v32, v62
	v_mul_f32_e32 v32, 0x3f4c422a, v32
	v_add_f32_e32 v32, v32, v32
	v_mul_f32_e32 v32, 0x3fb8aa3b, v32
	v_exp_f32_e32 v32, v32
	v_mul_f32_e32 v37, 0.5, v62
	v_add_f32_e32 v32, 1.0, v32
	v_rcp_f32_e32 v32, v32
	s_nop 0
	v_fma_f32 v32, v32, -2.0, 1.0
	v_add_f32_e32 v32, 1.0, v32
	v_mul_f32_e32 v32, v37, v32
	v_mul_f32_e32 v37, 0x3d372713, v63
	v_mul_f32_e32 v37, v63, v37
	v_fma_f32 v37, v63, v37, v63
	v_mul_f32_e32 v37, 0x3f4c422a, v37
	v_add_f32_e32 v37, v37, v37
	v_mul_f32_e32 v37, 0x3fb8aa3b, v37
	v_exp_f32_e32 v37, v37
	s_nop 0
	v_add_f32_e32 v37, 1.0, v37
	v_rcp_f32_e32 v37, v37
	s_nop 0
	v_fma_f32 v37, v37, -2.0, 1.0
	v_add_f32_e32 v37, 1.0, v37
	v_mul_f32_e32 v37, v38, v37
	v_cvt_pk_bf16_f32 v37, v32, v37
	v_mul_f32_e32 v32, 0x3d372713, v16
	v_mul_f32_e32 v32, v16, v32
	v_fma_f32 v32, v16, v32, v16
	v_mul_f32_e32 v32, 0x3f4c422a, v32
	v_add_f32_e32 v32, v32, v32
	v_mul_f32_e32 v32, 0x3fb8aa3b, v32
	v_exp_f32_e32 v32, v32
	v_mul_f32_e32 v16, 0.5, v16
	global_store_dwordx2 v[34:35], v[36:37], off offset:16
	v_mov_b32_e32 v35, s11
	v_add_f32_e32 v32, 1.0, v32
	v_rcp_f32_e32 v32, v32
	v_or_b32_e32 v34, s10, v140
	v_lshl_add_u64 v[36:37], v[34:35], 0, v[114:115]
	v_fma_f32 v32, v32, -2.0, 1.0
	v_add_f32_e32 v32, 1.0, v32
	v_mul_f32_e32 v16, v16, v32
	v_mul_f32_e32 v32, 0x3d372713, v17
	v_mul_f32_e32 v32, v17, v32
	v_fma_f32 v32, v17, v32, v17
	v_mul_f32_e32 v32, 0x3f4c422a, v32
	v_add_f32_e32 v32, v32, v32
	v_mul_f32_e32 v32, 0x3fb8aa3b, v32
	v_exp_f32_e32 v32, v32
	v_mul_f32_e32 v17, 0.5, v17
	v_add_f32_e32 v32, 1.0, v32
	v_rcp_f32_e32 v32, v32
	s_nop 0
	v_fma_f32 v32, v32, -2.0, 1.0
	v_add_f32_e32 v32, 1.0, v32
	v_mul_f32_e32 v17, v17, v32
	v_cvt_pk_bf16_f32 v16, v16, v17
	v_mul_f32_e32 v17, 0x3d372713, v18
	v_mul_f32_e32 v17, v18, v17
	v_fma_f32 v17, v18, v17, v18
	v_mul_f32_e32 v17, 0x3f4c422a, v17
	v_add_f32_e32 v17, v17, v17
	v_mul_f32_e32 v17, 0x3fb8aa3b, v17
	v_exp_f32_e32 v17, v17
	v_mul_f32_e32 v18, 0.5, v18
	v_add_f32_e32 v17, 1.0, v17
	v_rcp_f32_e32 v17, v17
	s_nop 0
	v_fma_f32 v17, v17, -2.0, 1.0
	v_add_f32_e32 v17, 1.0, v17
	v_mul_f32_e32 v17, v18, v17
	v_mul_f32_e32 v18, 0x3d372713, v19
	v_mul_f32_e32 v18, v19, v18
	v_fma_f32 v18, v19, v18, v19
	v_mul_f32_e32 v18, 0x3f4c422a, v18
	v_add_f32_e32 v18, v18, v18
	v_mul_f32_e32 v18, 0x3fb8aa3b, v18
	v_exp_f32_e32 v18, v18
	v_mul_f32_e32 v19, 0.5, v19
	v_add_f32_e32 v18, 1.0, v18
	v_rcp_f32_e32 v18, v18
	s_nop 0
	v_fma_f32 v18, v18, -2.0, 1.0
	v_add_f32_e32 v18, 1.0, v18
	v_mul_f32_e32 v18, v19, v18
	v_cvt_pk_bf16_f32 v17, v17, v18
	v_lshlrev_b64 v[18:19], 10, v[36:37]
	v_lshl_add_u64 v[18:19], s[8:9], 0, v[18:19]
	v_lshl_add_u64 v[18:19], v[18:19], 0, v[146:147]
	global_store_dwordx2 v[18:19], v[16:17], off
	v_mul_f32_e32 v16, 0x3d372713, v20
	v_mul_f32_e32 v16, v20, v16
	v_fma_f32 v16, v20, v16, v20
	v_mul_f32_e32 v16, 0x3f4c422a, v16
	v_add_f32_e32 v16, v16, v16
	v_mul_f32_e32 v16, 0x3fb8aa3b, v16
	v_exp_f32_e32 v16, v16
	v_mul_f32_e32 v17, 0.5, v20
	v_mul_f32_e32 v20, 0.5, v21
	v_add_f32_e32 v16, 1.0, v16
	v_rcp_f32_e32 v16, v16
	s_nop 0
	v_fma_f32 v16, v16, -2.0, 1.0
	v_add_f32_e32 v16, 1.0, v16
	v_mul_f32_e32 v16, v17, v16
	v_mul_f32_e32 v17, 0x3d372713, v21
	v_mul_f32_e32 v17, v21, v17
	v_fma_f32 v17, v21, v17, v21
	v_mul_f32_e32 v17, 0x3f4c422a, v17
	v_add_f32_e32 v17, v17, v17
	v_mul_f32_e32 v17, 0x3fb8aa3b, v17
	v_exp_f32_e32 v17, v17
	v_mul_f32_e32 v21, 0.5, v23
	v_add_f32_e32 v17, 1.0, v17
	v_rcp_f32_e32 v17, v17
	s_nop 0
	v_fma_f32 v17, v17, -2.0, 1.0
	v_add_f32_e32 v17, 1.0, v17
	v_mul_f32_e32 v17, v20, v17
	v_cvt_pk_bf16_f32 v16, v16, v17
	v_mul_f32_e32 v17, 0x3d372713, v22
	v_mul_f32_e32 v17, v22, v17
	v_fma_f32 v17, v22, v17, v22
	v_mul_f32_e32 v17, 0x3f4c422a, v17
	v_add_f32_e32 v17, v17, v17
	v_mul_f32_e32 v17, 0x3fb8aa3b, v17
	v_exp_f32_e32 v17, v17
	v_mul_f32_e32 v20, 0.5, v22
	v_add_f32_e32 v17, 1.0, v17
	v_rcp_f32_e32 v17, v17
	s_nop 0
	v_fma_f32 v17, v17, -2.0, 1.0
	v_add_f32_e32 v17, 1.0, v17
	v_mul_f32_e32 v17, v20, v17
	v_mul_f32_e32 v20, 0x3d372713, v23
	v_mul_f32_e32 v20, v23, v20
	v_fma_f32 v20, v23, v20, v23
	v_mul_f32_e32 v20, 0x3f4c422a, v20
	v_add_f32_e32 v20, v20, v20
	v_mul_f32_e32 v20, 0x3fb8aa3b, v20
	v_exp_f32_e32 v20, v20
	s_nop 0
	v_add_f32_e32 v20, 1.0, v20
	v_rcp_f32_e32 v20, v20
	s_nop 0
	v_fma_f32 v20, v20, -2.0, 1.0
	v_add_f32_e32 v20, 1.0, v20
	v_mul_f32_e32 v20, v21, v20
	v_cvt_pk_bf16_f32 v17, v17, v20
	global_store_dwordx2 v[18:19], v[16:17], off offset:16
	v_mul_f32_e32 v18, 0x3d372713, v24
	v_mul_f32_e32 v18, v24, v18
	v_fma_f32 v18, v24, v18, v24
	v_mul_f32_e32 v18, 0x3f4c422a, v18
	v_add_f32_e32 v18, v18, v18
	v_mul_f32_e32 v18, 0x3fb8aa3b, v18
	v_exp_f32_e32 v18, v18
	v_mul_f32_e32 v19, 0.5, v24
	v_mul_f32_e32 v20, 0.5, v25
	v_lshl_add_u64 v[16:17], v[34:35], 0, v[136:137]
	v_add_f32_e32 v18, 1.0, v18
	v_rcp_f32_e32 v18, v18
	v_lshlrev_b64 v[16:17], 10, v[16:17]
	v_lshl_add_u64 v[16:17], s[8:9], 0, v[16:17]
	v_mul_f32_e32 v21, 0.5, v27
	v_fma_f32 v18, v18, -2.0, 1.0
	v_add_f32_e32 v18, 1.0, v18
	v_mul_f32_e32 v18, v19, v18
	v_mul_f32_e32 v19, 0x3d372713, v25
	v_mul_f32_e32 v19, v25, v19
	v_fma_f32 v19, v25, v19, v25
	v_mul_f32_e32 v19, 0x3f4c422a, v19
	v_add_f32_e32 v19, v19, v19
	v_mul_f32_e32 v19, 0x3fb8aa3b, v19
	v_exp_f32_e32 v19, v19
	v_lshl_add_u64 v[16:17], v[16:17], 0, v[146:147]
	v_add_f32_e32 v19, 1.0, v19
	v_rcp_f32_e32 v19, v19
	s_nop 0
	v_fma_f32 v19, v19, -2.0, 1.0
	v_add_f32_e32 v19, 1.0, v19
	v_mul_f32_e32 v19, v20, v19
	v_cvt_pk_bf16_f32 v18, v18, v19
	v_mul_f32_e32 v19, 0x3d372713, v26
	v_mul_f32_e32 v19, v26, v19
	v_fma_f32 v19, v26, v19, v26
	v_mul_f32_e32 v19, 0x3f4c422a, v19
	v_add_f32_e32 v19, v19, v19
	v_mul_f32_e32 v19, 0x3fb8aa3b, v19
	v_exp_f32_e32 v19, v19
	v_mul_f32_e32 v20, 0.5, v26
	v_add_f32_e32 v19, 1.0, v19
	v_rcp_f32_e32 v19, v19
	s_nop 0
	v_fma_f32 v19, v19, -2.0, 1.0
	v_add_f32_e32 v19, 1.0, v19
	v_mul_f32_e32 v19, v20, v19
	v_mul_f32_e32 v20, 0x3d372713, v27
	v_mul_f32_e32 v20, v27, v20
	v_fma_f32 v20, v27, v20, v27
	v_mul_f32_e32 v20, 0x3f4c422a, v20
	v_add_f32_e32 v20, v20, v20
	v_mul_f32_e32 v20, 0x3fb8aa3b, v20
	v_exp_f32_e32 v20, v20
	s_nop 0
	v_add_f32_e32 v20, 1.0, v20
	v_rcp_f32_e32 v20, v20
	s_nop 0
	v_fma_f32 v20, v20, -2.0, 1.0
	v_add_f32_e32 v20, 1.0, v20
	v_mul_f32_e32 v20, v21, v20
	v_cvt_pk_bf16_f32 v19, v19, v20
	global_store_dwordx2 v[16:17], v[18:19], off
	v_mul_f32_e32 v18, 0x3d372713, v28
	v_mul_f32_e32 v18, v28, v18
	v_fma_f32 v18, v28, v18, v28
	v_mul_f32_e32 v18, 0x3f4c422a, v18
	v_add_f32_e32 v18, v18, v18
	v_mul_f32_e32 v18, 0x3fb8aa3b, v18
	v_exp_f32_e32 v18, v18
	v_mul_f32_e32 v19, 0.5, v28
	v_mul_f32_e32 v20, 0.5, v29
	v_mul_f32_e32 v21, 0.5, v31
	v_add_f32_e32 v18, 1.0, v18
	v_rcp_f32_e32 v18, v18
	s_nop 0
	v_fma_f32 v18, v18, -2.0, 1.0
	v_add_f32_e32 v18, 1.0, v18
	v_mul_f32_e32 v18, v19, v18
	v_mul_f32_e32 v19, 0x3d372713, v29
	v_mul_f32_e32 v19, v29, v19
	v_fma_f32 v19, v29, v19, v29
	v_mul_f32_e32 v19, 0x3f4c422a, v19
	v_add_f32_e32 v19, v19, v19
	v_mul_f32_e32 v19, 0x3fb8aa3b, v19
	v_exp_f32_e32 v19, v19
	s_nop 0
	v_add_f32_e32 v19, 1.0, v19
	v_rcp_f32_e32 v19, v19
	s_nop 0
	v_fma_f32 v19, v19, -2.0, 1.0
	v_add_f32_e32 v19, 1.0, v19
	v_mul_f32_e32 v19, v20, v19
	v_cvt_pk_bf16_f32 v18, v18, v19
	v_mul_f32_e32 v19, 0x3d372713, v30
	v_mul_f32_e32 v19, v30, v19
	v_fma_f32 v19, v30, v19, v30
	v_mul_f32_e32 v19, 0x3f4c422a, v19
	v_add_f32_e32 v19, v19, v19
	v_mul_f32_e32 v19, 0x3fb8aa3b, v19
	v_exp_f32_e32 v19, v19
	v_mul_f32_e32 v20, 0.5, v30
	v_add_f32_e32 v19, 1.0, v19
	v_rcp_f32_e32 v19, v19
	s_nop 0
	v_fma_f32 v19, v19, -2.0, 1.0
	v_add_f32_e32 v19, 1.0, v19
	v_mul_f32_e32 v19, v20, v19
	v_mul_f32_e32 v20, 0x3d372713, v31
	v_mul_f32_e32 v20, v31, v20
	v_fma_f32 v20, v31, v20, v31
	v_mul_f32_e32 v20, 0x3f4c422a, v20
	v_add_f32_e32 v20, v20, v20
	v_mul_f32_e32 v20, 0x3fb8aa3b, v20
	v_exp_f32_e32 v20, v20
	s_nop 0
	v_add_f32_e32 v20, 1.0, v20
	v_rcp_f32_e32 v20, v20
	s_nop 0
	v_fma_f32 v20, v20, -2.0, 1.0
	v_add_f32_e32 v20, 1.0, v20
	v_mul_f32_e32 v20, v21, v20
	v_cvt_pk_bf16_f32 v19, v19, v20
	v_mul_f32_e32 v20, 0x3d372713, v0
	v_mul_f32_e32 v20, v0, v20
	v_fma_f32 v20, v0, v20, v0
	v_mul_f32_e32 v20, 0x3f4c422a, v20
	v_add_f32_e32 v20, v20, v20
	v_mul_f32_e32 v20, 0x3fb8aa3b, v20
	v_exp_f32_e32 v20, v20
	v_mul_f32_e32 v0, 0.5, v0
	global_store_dwordx2 v[16:17], v[18:19], off offset:16
	v_mov_b32_e32 v17, s11
	v_add_f32_e32 v20, 1.0, v20
	v_rcp_f32_e32 v20, v20
	v_or_b32_e32 v16, s10, v142
	v_lshl_add_u64 v[18:19], v[16:17], 0, v[114:115]
	v_fma_f32 v20, v20, -2.0, 1.0
	v_add_f32_e32 v20, 1.0, v20
	v_mul_f32_e32 v0, v0, v20
	v_mul_f32_e32 v20, 0x3d372713, v1
	v_mul_f32_e32 v20, v1, v20
	v_fma_f32 v20, v1, v20, v1
	v_mul_f32_e32 v20, 0x3f4c422a, v20
	v_add_f32_e32 v20, v20, v20
	v_mul_f32_e32 v20, 0x3fb8aa3b, v20
	v_exp_f32_e32 v20, v20
	v_mul_f32_e32 v1, 0.5, v1
	v_add_f32_e32 v20, 1.0, v20
	v_rcp_f32_e32 v20, v20
	s_nop 0
	v_fma_f32 v20, v20, -2.0, 1.0
	v_add_f32_e32 v20, 1.0, v20
	v_mul_f32_e32 v1, v1, v20
	v_cvt_pk_bf16_f32 v0, v0, v1
	v_mul_f32_e32 v1, 0x3d372713, v2
	v_mul_f32_e32 v1, v2, v1
	v_fma_f32 v1, v2, v1, v2
	v_mul_f32_e32 v1, 0x3f4c422a, v1
	v_add_f32_e32 v1, v1, v1
	v_mul_f32_e32 v1, 0x3fb8aa3b, v1
	v_exp_f32_e32 v1, v1
	v_mul_f32_e32 v2, 0.5, v2
	v_add_f32_e32 v1, 1.0, v1
	v_rcp_f32_e32 v1, v1
	s_nop 0
	v_fma_f32 v1, v1, -2.0, 1.0
	v_add_f32_e32 v1, 1.0, v1
	v_mul_f32_e32 v1, v2, v1
	v_mul_f32_e32 v2, 0x3d372713, v3
	v_mul_f32_e32 v2, v3, v2
	v_fma_f32 v2, v3, v2, v3
	v_mul_f32_e32 v2, 0x3f4c422a, v2
	v_add_f32_e32 v2, v2, v2
	v_mul_f32_e32 v2, 0x3fb8aa3b, v2
	v_exp_f32_e32 v2, v2
	v_mul_f32_e32 v3, 0.5, v3
	v_add_f32_e32 v2, 1.0, v2
	v_rcp_f32_e32 v2, v2
	s_nop 0
	v_fma_f32 v2, v2, -2.0, 1.0
	v_add_f32_e32 v2, 1.0, v2
	v_mul_f32_e32 v2, v3, v2
	v_cvt_pk_bf16_f32 v1, v1, v2
	v_lshlrev_b64 v[2:3], 10, v[18:19]
	v_lshl_add_u64 v[2:3], s[8:9], 0, v[2:3]
	v_lshl_add_u64 v[2:3], v[2:3], 0, v[146:147]
	global_store_dwordx2 v[2:3], v[0:1], off
	v_mul_f32_e32 v0, 0x3d372713, v4
	v_mul_f32_e32 v0, v4, v0
	v_fma_f32 v0, v4, v0, v4
	v_mul_f32_e32 v0, 0x3f4c422a, v0
	v_add_f32_e32 v0, v0, v0
	v_mul_f32_e32 v0, 0x3fb8aa3b, v0
	v_exp_f32_e32 v0, v0
	v_mul_f32_e32 v1, 0.5, v4
	v_mul_f32_e32 v4, 0.5, v5
	v_add_f32_e32 v0, 1.0, v0
	v_rcp_f32_e32 v0, v0
	s_nop 0
	v_fma_f32 v0, v0, -2.0, 1.0
	v_add_f32_e32 v0, 1.0, v0
	v_mul_f32_e32 v0, v1, v0
	v_mul_f32_e32 v1, 0x3d372713, v5
	v_mul_f32_e32 v1, v5, v1
	v_fma_f32 v1, v5, v1, v5
	v_mul_f32_e32 v1, 0x3f4c422a, v1
	v_add_f32_e32 v1, v1, v1
	v_mul_f32_e32 v1, 0x3fb8aa3b, v1
	v_exp_f32_e32 v1, v1
	v_mul_f32_e32 v5, 0.5, v7
	v_add_f32_e32 v1, 1.0, v1
	v_rcp_f32_e32 v1, v1
	s_nop 0
	v_fma_f32 v1, v1, -2.0, 1.0
	v_add_f32_e32 v1, 1.0, v1
	v_mul_f32_e32 v1, v4, v1
	v_cvt_pk_bf16_f32 v0, v0, v1
	v_mul_f32_e32 v1, 0x3d372713, v6
	v_mul_f32_e32 v1, v6, v1
	v_fma_f32 v1, v6, v1, v6
	v_mul_f32_e32 v1, 0x3f4c422a, v1
	v_add_f32_e32 v1, v1, v1
	v_mul_f32_e32 v1, 0x3fb8aa3b, v1
	v_exp_f32_e32 v1, v1
	v_mul_f32_e32 v4, 0.5, v6
	v_add_f32_e32 v1, 1.0, v1
	v_rcp_f32_e32 v1, v1
	s_nop 0
	v_fma_f32 v1, v1, -2.0, 1.0
	v_add_f32_e32 v1, 1.0, v1
	v_mul_f32_e32 v1, v4, v1
	v_mul_f32_e32 v4, 0x3d372713, v7
	v_mul_f32_e32 v4, v7, v4
	v_fma_f32 v4, v7, v4, v7
	v_mul_f32_e32 v4, 0x3f4c422a, v4
	v_add_f32_e32 v4, v4, v4
	v_mul_f32_e32 v4, 0x3fb8aa3b, v4
	v_exp_f32_e32 v4, v4
	s_nop 0
	v_add_f32_e32 v4, 1.0, v4
	v_rcp_f32_e32 v4, v4
	s_nop 0
	v_fma_f32 v4, v4, -2.0, 1.0
	v_add_f32_e32 v4, 1.0, v4
	v_mul_f32_e32 v4, v5, v4
	v_cvt_pk_bf16_f32 v1, v1, v4
	global_store_dwordx2 v[2:3], v[0:1], off offset:16
	v_mul_f32_e32 v2, 0x3d372713, v8
	v_mul_f32_e32 v2, v8, v2
	v_fma_f32 v2, v8, v2, v8
	v_mul_f32_e32 v2, 0x3f4c422a, v2
	v_add_f32_e32 v2, v2, v2
	v_mul_f32_e32 v2, 0x3fb8aa3b, v2
	v_exp_f32_e32 v2, v2
	v_mul_f32_e32 v3, 0.5, v8
	v_mul_f32_e32 v4, 0.5, v9
	v_lshl_add_u64 v[0:1], v[16:17], 0, v[136:137]
	v_add_f32_e32 v2, 1.0, v2
	v_rcp_f32_e32 v2, v2
	v_lshlrev_b64 v[0:1], 10, v[0:1]
	v_lshl_add_u64 v[0:1], s[8:9], 0, v[0:1]
	v_mul_f32_e32 v5, 0.5, v11
	v_fma_f32 v2, v2, -2.0, 1.0
	v_add_f32_e32 v2, 1.0, v2
	v_mul_f32_e32 v2, v3, v2
	v_mul_f32_e32 v3, 0x3d372713, v9
	v_mul_f32_e32 v3, v9, v3
	v_fma_f32 v3, v9, v3, v9
	v_mul_f32_e32 v3, 0x3f4c422a, v3
	v_add_f32_e32 v3, v3, v3
	v_mul_f32_e32 v3, 0x3fb8aa3b, v3
	v_exp_f32_e32 v3, v3
	v_lshl_add_u64 v[0:1], v[0:1], 0, v[146:147]
	v_add_f32_e32 v3, 1.0, v3
	v_rcp_f32_e32 v3, v3
	s_nop 0
	v_fma_f32 v3, v3, -2.0, 1.0
	v_add_f32_e32 v3, 1.0, v3
	v_mul_f32_e32 v3, v4, v3
	v_cvt_pk_bf16_f32 v2, v2, v3
	v_mul_f32_e32 v3, 0x3d372713, v10
	v_mul_f32_e32 v3, v10, v3
	v_fma_f32 v3, v10, v3, v10
	v_mul_f32_e32 v3, 0x3f4c422a, v3
	v_add_f32_e32 v3, v3, v3
	v_mul_f32_e32 v3, 0x3fb8aa3b, v3
	v_exp_f32_e32 v3, v3
	v_mul_f32_e32 v4, 0.5, v10
	v_add_f32_e32 v3, 1.0, v3
	v_rcp_f32_e32 v3, v3
	s_nop 0
	v_fma_f32 v3, v3, -2.0, 1.0
	v_add_f32_e32 v3, 1.0, v3
	v_mul_f32_e32 v3, v4, v3
	v_mul_f32_e32 v4, 0x3d372713, v11
	v_mul_f32_e32 v4, v11, v4
	v_fma_f32 v4, v11, v4, v11
	v_mul_f32_e32 v4, 0x3f4c422a, v4
	v_add_f32_e32 v4, v4, v4
	v_mul_f32_e32 v4, 0x3fb8aa3b, v4
	v_exp_f32_e32 v4, v4
	s_nop 0
	v_add_f32_e32 v4, 1.0, v4
	v_rcp_f32_e32 v4, v4
	s_nop 0
	v_fma_f32 v4, v4, -2.0, 1.0
	v_add_f32_e32 v4, 1.0, v4
	v_mul_f32_e32 v4, v5, v4
	v_cvt_pk_bf16_f32 v3, v3, v4
	global_store_dwordx2 v[0:1], v[2:3], off
	v_mul_f32_e32 v2, 0x3d372713, v12
	v_mul_f32_e32 v2, v12, v2
	v_fma_f32 v2, v12, v2, v12
	v_mul_f32_e32 v2, 0x3f4c422a, v2
	v_add_f32_e32 v2, v2, v2
	v_mul_f32_e32 v2, 0x3fb8aa3b, v2
	v_exp_f32_e32 v2, v2
	v_mul_f32_e32 v3, 0.5, v12
	v_mul_f32_e32 v4, 0.5, v13
	v_mul_f32_e32 v5, 0.5, v15
	v_add_f32_e32 v2, 1.0, v2
	v_rcp_f32_e32 v2, v2
	s_nop 0
	v_fma_f32 v2, v2, -2.0, 1.0
	v_add_f32_e32 v2, 1.0, v2
	v_mul_f32_e32 v2, v3, v2
	v_mul_f32_e32 v3, 0x3d372713, v13
	v_mul_f32_e32 v3, v13, v3
	v_fma_f32 v3, v13, v3, v13
	v_mul_f32_e32 v3, 0x3f4c422a, v3
	v_add_f32_e32 v3, v3, v3
	v_mul_f32_e32 v3, 0x3fb8aa3b, v3
	v_exp_f32_e32 v3, v3
	s_nop 0
	v_add_f32_e32 v3, 1.0, v3
	v_rcp_f32_e32 v3, v3
	s_nop 0
	v_fma_f32 v3, v3, -2.0, 1.0
	v_add_f32_e32 v3, 1.0, v3
	v_mul_f32_e32 v3, v4, v3
	v_cvt_pk_bf16_f32 v2, v2, v3
	v_mul_f32_e32 v3, 0x3d372713, v14
	v_mul_f32_e32 v3, v14, v3
	v_fma_f32 v3, v14, v3, v14
	v_mul_f32_e32 v3, 0x3f4c422a, v3
	v_add_f32_e32 v3, v3, v3
	v_mul_f32_e32 v3, 0x3fb8aa3b, v3
	v_exp_f32_e32 v3, v3
	v_mul_f32_e32 v4, 0.5, v14
	v_add_f32_e32 v3, 1.0, v3
	v_rcp_f32_e32 v3, v3
	s_nop 0
	v_fma_f32 v3, v3, -2.0, 1.0
	v_add_f32_e32 v3, 1.0, v3
	v_mul_f32_e32 v3, v4, v3
	v_mul_f32_e32 v4, 0x3d372713, v15
	v_mul_f32_e32 v4, v15, v4
	v_fma_f32 v4, v15, v4, v15
	v_mul_f32_e32 v4, 0x3f4c422a, v4
	v_add_f32_e32 v4, v4, v4
	v_mul_f32_e32 v4, 0x3fb8aa3b, v4
	v_exp_f32_e32 v4, v4
	s_nop 0
	v_add_f32_e32 v4, 1.0, v4
	v_rcp_f32_e32 v4, v4
	s_nop 0
	v_fma_f32 v4, v4, -2.0, 1.0
	v_add_f32_e32 v4, 1.0, v4
	v_mul_f32_e32 v4, v5, v4
	v_cvt_pk_bf16_f32 v3, v3, v4
	global_store_dwordx2 v[0:1], v[2:3], off offset:16
	s_cbranch_scc0 .LBB0_718
